# ret_out: gate prefetch moved ahead of the cross-chunk loop so its latency overlaps the loop
# baseline (speedup 1.0000x reference)
; __device__ __forceinline__ unsigned pk2(float lo, float hi) { return pg8::pk_bf16_rne(lo, hi); }
; __device__ __forceinline__ int crow(int r, int hi) { return (r & 3) + 8 * (r >> 2) + 4 * hi; }
; #define MFMA32(a, b, c) __builtin_amdgcn_mfma_f32_32x32x16_bf16((a), (b), (c), 0, 0, 0)
; __device__ __forceinline__ void ret_out(const Params& P, int l, unsigned char* lds, int u, int tid) {
;     ...
;     for (int kb = 0; kb < 4; ++kb) {
;         f32x16 p;
; #pragma unroll
;         for (int i = 0; i < 16; ++i) p[i] = 0.f;
; #pragma unroll
;         for (int s = 0; s < 4; ++s) { const bf16x8 a = *(const bf16x8*)(Kc + (32 * kb + r32) * RK + 16 * s + 8 * hi); p = MFMA32(a, qr[s], p); }
; #pragma unroll
;         for (int r = 0; r < 16; ++r) { const int mkey = 32 * kb + crow(r, hi); const int df = cq - mkey;
;             const float wgt = df >= 0 ? __builtin_amdgcn_exp2f(lgf2 * (float)df) : __builtin_amdgcn_exp2f(lgb2 * (float)(-df)); p[r] *= wgt; }
; #pragma unroll
;         for (int hf = 0; hf < 2; ++hf) {
;             u32x4 w; w.x = pk2(p[8 * hf + 0], p[8 * hf + 1]); w.y = pk2(p[8 * hf + 2], p[8 * hf + 3]); w.z = pk2(p[8 * hf + 4], p[8 * hf + 5]); w.w = pk2(p[8 * hf + 6], p[8 * hf + 7]);
;             const bf16x8 A = __builtin_bit_cast(bf16x8, w);
;             const int kofs = 32 * kb + 16 * hf + 4 * hi;
;             const s16x4 l0 = *(const s16x4*)(Vc + r32 * RS + kofs), h0 = *(const s16x4*)(Vc + r32 * RS + kofs + 8);
;             const s16x4 l1 = *(const s16x4*)(Vc + (32 + r32) * RS + kofs), h1 = *(const s16x4*)(Vc + (32 + r32) * RS + kofs + 8);
;             const bf16x8 B0 = __builtin_shufflevector(l0, h0, 0, 1, 2, 3, 4, 5, 6, 7), B1 = __builtin_shufflevector(l1, h1, 0, 1, 2, 3, 4, 5, 6, 7);
;             o0 = MFMA32(A, B0, o0); o1 = MFMA32(A, B1, o1);
;         }
;     }
.LBB0_143:
	ds_read_b128 v[32:35], v84
	ds_read_b128 v[70:73], v84 offset:32
	v_add_u32_e32 v76, s18, v86
	v_cmp_gt_i32_e32 vcc, 0, v76
	v_add_u32_e32 v87, 0x2000, v85
	s_waitcnt vmcnt(3) lgkmcnt(1)
	v_mfma_f32_32x32x16_bf16 v[32:47], v[32:35], v[60:63], 0
	s_sub_i32 s18, s18, 32
	s_cmpk_lg_i32 s18, 0xff80
	s_waitcnt vmcnt(2) lgkmcnt(0)
	v_mfma_f32_32x32x16_bf16 v[32:47], v[70:73], v[56:59], v[32:47]
	ds_read_b128 v[70:73], v84 offset:64
	s_waitcnt vmcnt(1) lgkmcnt(0)
	v_mfma_f32_32x32x16_bf16 v[32:47], v[70:73], v[52:55], v[32:47]
	ds_read_b128 v[70:73], v84 offset:96
	v_add_u32_e32 v84, 0x1200, v84
	s_waitcnt vmcnt(0) lgkmcnt(0)
	v_mfma_f32_32x32x16_bf16 v[32:47], v[70:73], v[48:51], v[32:47]
	v_sub_u32_e32 v70, 0, v76
	v_max_i32_e32 v70, v76, v70
	v_cvt_f32_u32_e32 v70, v70
	v_cndmask_b32_e32 v71, v82, v83, vcc
	v_sub_u32_e32 v72, 1, v76
	v_mul_f32_e32 v70, v71, v70
	v_add_u32_e32 v71, -1, v76
	v_max_i32_e32 v72, v71, v72
	v_cvt_f32_u32_e32 v72, v72
	v_cmp_gt_i32_e32 vcc, 0, v71
	v_exp_f32_e32 v70, v70
	s_nop 0
	v_cndmask_b32_e32 v71, v82, v83, vcc
	v_mul_f32_e32 v71, v71, v72
	v_exp_f32_e32 v71, v71
	v_sub_u32_e32 v72, 3, v76
	v_pk_mul_f32 v[32:33], v[70:71], v[32:33]
	v_add_u32_e32 v70, -2, v76
	v_sub_u32_e32 v71, 2, v76
	v_max_i32_e32 v71, v70, v71
	v_cvt_f32_u32_e32 v71, v71
	v_cmp_gt_i32_e32 vcc, 0, v70
	v_cvt_pk_bf16_f32 v32, v32, v33
	s_nop 0
	v_cndmask_b32_e32 v70, v82, v83, vcc
	v_mul_f32_e32 v70, v70, v71
	v_add_u32_e32 v71, -3, v76
	v_max_i32_e32 v72, v71, v72
	v_cvt_f32_u32_e32 v72, v72
	v_cmp_gt_i32_e32 vcc, 0, v71
	v_exp_f32_e32 v70, v70
	s_nop 0
	v_cndmask_b32_e32 v71, v82, v83, vcc
	v_mul_f32_e32 v71, v71, v72
	v_exp_f32_e32 v71, v71
	v_sub_u32_e32 v72, 9, v76
	v_pk_mul_f32 v[34:35], v[70:71], v[34:35]
	v_add_u32_e32 v70, -8, v76
	v_sub_u32_e32 v71, 8, v76
	v_max_i32_e32 v71, v70, v71
	v_cvt_f32_u32_e32 v71, v71
	v_cmp_gt_i32_e32 vcc, 0, v70
	v_cvt_pk_bf16_f32 v33, v34, v35
	s_nop 0
	v_cndmask_b32_e32 v70, v82, v83, vcc
	v_mul_f32_e32 v70, v70, v71
	v_add_u32_e32 v71, -9, v76
	v_max_i32_e32 v72, v71, v72
	v_cvt_f32_u32_e32 v72, v72
	v_cmp_gt_i32_e32 vcc, 0, v71
	v_exp_f32_e32 v70, v70
	s_nop 0
	v_cndmask_b32_e32 v71, v82, v83, vcc
	v_mul_f32_e32 v71, v71, v72
	v_exp_f32_e32 v71, v71
	v_sub_u32_e32 v72, 11, v76
	v_pk_mul_f32 v[36:37], v[70:71], v[36:37]
	v_add_u32_e32 v70, -10, v76
	v_sub_u32_e32 v71, 10, v76
	v_max_i32_e32 v71, v70, v71
	v_cvt_f32_u32_e32 v71, v71
	v_cmp_gt_i32_e32 vcc, 0, v70
	v_cvt_pk_bf16_f32 v34, v36, v37
	s_nop 0
	v_cndmask_b32_e32 v70, v82, v83, vcc
	v_mul_f32_e32 v70, v70, v71
	v_add_u32_e32 v71, -11, v76
	v_max_i32_e32 v72, v71, v72
	v_cvt_f32_u32_e32 v72, v72
	v_cmp_gt_i32_e32 vcc, 0, v71
	v_exp_f32_e32 v70, v70
	s_nop 0
	v_cndmask_b32_e32 v71, v82, v83, vcc
	v_mul_f32_e32 v71, v71, v72
	v_exp_f32_e32 v71, v71
	v_sub_u32_e32 v72, 17, v76
	v_pk_mul_f32 v[38:39], v[70:71], v[38:39]
	v_add_u32_e32 v70, -16, v76
	v_sub_u32_e32 v71, 16, v76
	v_max_i32_e32 v71, v70, v71
	v_cvt_f32_u32_e32 v71, v71
	v_cmp_gt_i32_e32 vcc, 0, v70
	v_cvt_pk_bf16_f32 v35, v38, v39
	s_nop 0
	v_cndmask_b32_e32 v70, v82, v83, vcc
	v_mul_f32_e32 v70, v70, v71
	v_subrev_u32_e32 v71, 17, v76
	v_max_i32_e32 v72, v71, v72
	v_cvt_f32_u32_e32 v72, v72
	v_cmp_gt_i32_e32 vcc, 0, v71
	v_exp_f32_e32 v70, v70
	s_nop 0
	v_cndmask_b32_e32 v71, v82, v83, vcc
	v_mul_f32_e32 v71, v71, v72
	v_exp_f32_e32 v71, v71
	v_sub_u32_e32 v72, 19, v76
	v_pk_mul_f32 v[70:71], v[70:71], v[40:41]
	v_subrev_u32_e32 v40, 18, v76
	v_sub_u32_e32 v41, 18, v76
	v_max_i32_e32 v41, v40, v41
	v_cvt_f32_u32_e32 v41, v41
	v_cmp_gt_i32_e32 vcc, 0, v40
	s_nop 1
	v_cndmask_b32_e32 v40, v82, v83, vcc
	v_mul_f32_e32 v40, v40, v41
	v_subrev_u32_e32 v41, 19, v76
	v_max_i32_e32 v72, v41, v72
	v_cvt_f32_u32_e32 v72, v72
	v_cmp_gt_i32_e32 vcc, 0, v41
	v_exp_f32_e32 v40, v40
	s_nop 0
	v_cndmask_b32_e32 v41, v82, v83, vcc
	v_mul_f32_e32 v41, v41, v72
	v_exp_f32_e32 v41, v41
	s_nop 0
	v_pk_mul_f32 v[72:73], v[40:41], v[42:43]
	v_subrev_u32_e32 v40, 24, v76
	v_sub_u32_e32 v41, 24, v76
	v_max_i32_e32 v41, v40, v41
	v_cvt_f32_u32_e32 v41, v41
	v_cmp_gt_i32_e32 vcc, 0, v40
	v_sub_u32_e32 v42, 25, v76
	s_nop 0
	v_cndmask_b32_e32 v40, v82, v83, vcc
	v_mul_f32_e32 v40, v40, v41
	v_subrev_u32_e32 v41, 25, v76
	v_max_i32_e32 v42, v41, v42
	v_cvt_f32_u32_e32 v42, v42
	v_cmp_gt_i32_e32 vcc, 0, v41
	v_exp_f32_e32 v40, v40
	s_nop 0
	v_cndmask_b32_e32 v41, v82, v83, vcc
	v_mul_f32_e32 v41, v41, v42
	v_exp_f32_e32 v41, v41
	v_sub_u32_e32 v42, 27, v76
	v_pk_mul_f32 v[74:75], v[40:41], v[44:45]
	v_subrev_u32_e32 v40, 26, v76
	v_sub_u32_e32 v41, 26, v76
	v_max_i32_e32 v41, v40, v41
	v_cvt_f32_u32_e32 v41, v41
	v_cmp_gt_i32_e32 vcc, 0, v40
	s_nop 1
	v_cndmask_b32_e32 v40, v82, v83, vcc
	v_mul_f32_e32 v40, v40, v41
	v_subrev_u32_e32 v41, 27, v76
	v_max_i32_e32 v42, v41, v42
	v_cvt_f32_u32_e32 v42, v42
	v_cmp_gt_i32_e32 vcc, 0, v41
	v_exp_f32_e32 v40, v40
	s_nop 0
	v_cndmask_b32_e32 v41, v82, v83, vcc
	v_mul_f32_e32 v41, v41, v42
	v_exp_f32_e32 v41, v41
	s_nop 0
	v_pk_mul_f32 v[76:77], v[40:41], v[46:47]
	ds_read2_b64 v[40:43], v87 offset0:64 offset1:66
	ds_read2_b64 v[44:47], v85 offset1:2
	ds_read2_b64 v[36:39], v85 offset0:4 offset1:6
	s_waitcnt lgkmcnt(1)
	v_mfma_f32_32x32x16_bf16 v[0:15], v[32:35], v[44:47], v[0:15]
	v_add_u32_e32 v85, 64, v85
	v_mfma_f32_32x32x16_bf16 v[16:31], v[32:35], v[40:43], v[16:31]
	v_cvt_pk_bf16_f32 v32, v70, v71
	v_cvt_pk_bf16_f32 v33, v72, v73
	v_cvt_pk_bf16_f32 v34, v74, v75
	v_cvt_pk_bf16_f32 v35, v76, v77
	ds_read2_b64 v[40:43], v87 offset0:68 offset1:70
	s_waitcnt lgkmcnt(1)
	v_mfma_f32_32x32x16_bf16 v[0:15], v[32:35], v[36:39], v[0:15]
	s_waitcnt lgkmcnt(0)
	v_mfma_f32_32x32x16_bf16 v[16:31], v[32:35], v[40:43], v[16:31]
	s_cbranch_scc1 .LBB0_143
; __device__ __forceinline__ unsigned pk2(float lo, float hi) { return pg8::pk_bf16_rne(lo, hi); }
; __device__ __forceinline__ float bf2f(unsigned short u) { return __uint_as_float(((unsigned)u) << 16); }
; __device__ __forceinline__ int crow(int r, int hi) { return (r & 3) + 8 * (r >> 2) + 4 * hi; }
; __device__ __forceinline__ void ret_out(const Params& P, int l, unsigned char* lds, int u, int tid) {
;     ...
;     const int unit = (b * 4 + h) * 32 + n;
; #pragma unroll 1
;     for (int dir = 0; dir < 2; ++dir) {
;         const bf16_t* Rt = RT + ((size_t)unit * 2 + dir) * 4096;
;         const float wq = dir == 0 ? __builtin_amdgcn_exp2f(lgf2 * (float)(cq + 1)) : __builtin_amdgcn_exp2f(lgb2 * (float)(128 - cq));
; #pragma unroll
;         for (int s = 0; s < 4; ++s) {
;             u32x4 w;
; #pragma unroll
;             for (int j = 0; j < 4; ++j) w[j] = pk2(bf2f((unsigned short)qr[s][2 * j]) * wq, bf2f((unsigned short)qr[s][2 * j + 1]) * wq);
;     ...
;         const size_t t = tc + c0f + crow(r, hi);
;         const float ga = bf2f(ZR[t * 1024 + 768 + h * 64 + r32]), gb = bf2f(ZR[t * 1024 + 768 + h * 64 + 32 + r32]);
	v_lshlrev_b32_e32 v32, 1, v79
	v_lshlrev_b32_e32 v33, 7, v67
	v_lshlrev_b32_e32 v34, 5, v78
	v_or3_b32 v32, v33, v32, v34
	v_sub_u32_e32 v34, 0x80, v80
	v_cvt_f32_ubyte0_e32 v34, v34
	v_mul_f32_e32 v34, v83, v34
	v_exp_f32_e32 v67, v34
	v_add_u32_e32 v34, 1, v80
	v_add_u32_e32 v32, v32, v81
	v_cvt_f32_ubyte0_e32 v34, v34
	v_ashrrev_i32_e32 v33, 31, v32
	v_mul_f32_e32 v34, v82, v34
	v_lshlrev_b64 v[32:33], 14, v[32:33]
	v_exp_f32_e32 v74, v34
	v_lshl_add_u64 v[32:33], s[92:93], 0, v[32:33]
	v_lshlrev_b32_e32 v152, 7, v222
	v_lshl_add_u64 v[32:33], v[32:33], 0, v[152:153]
	s_mov_b64 s[18:19], 0xa400000
	v_lshl_add_u64 v[32:33], v[32:33], 0, s[18:19]
	v_and_b32_e32 v35, 0xffff0000, v60
	v_lshlrev_b32_e32 v34, 16, v60
	v_and_b32_e32 v37, 0xffff0000, v61
	v_lshlrev_b32_e32 v36, 16, v61
	v_and_b32_e32 v39, 0xffff0000, v62
	v_lshlrev_b32_e32 v38, 16, v62
	v_and_b32_e32 v41, 0xffff0000, v63
	v_lshlrev_b32_e32 v40, 16, v63
	v_and_b32_e32 v43, 0xffff0000, v56
	v_lshlrev_b32_e32 v42, 16, v56
	v_and_b32_e32 v45, 0xffff0000, v57
	v_lshlrev_b32_e32 v44, 16, v57
	v_and_b32_e32 v47, 0xffff0000, v58
	v_lshlrev_b32_e32 v46, 16, v58
	v_and_b32_e32 v57, 0xffff0000, v59
	v_lshlrev_b32_e32 v56, 16, v59
	v_and_b32_e32 v59, 0xffff0000, v52
	v_lshlrev_b32_e32 v58, 16, v52
	v_and_b32_e32 v61, 0xffff0000, v53
	v_lshlrev_b32_e32 v60, 16, v53
	v_and_b32_e32 v53, 0xffff0000, v54
	v_lshlrev_b32_e32 v52, 16, v54
	v_and_b32_e32 v63, 0xffff0000, v55
	v_lshlrev_b32_e32 v62, 16, v55
	v_and_b32_e32 v55, 0xffff0000, v48
	v_lshlrev_b32_e32 v54, 16, v48
	v_and_b32_e32 v71, 0xffff0000, v49
	v_lshlrev_b32_e32 v70, 16, v49
	v_and_b32_e32 v49, 0xffff0000, v50
	v_lshlrev_b32_e32 v48, 16, v50
	v_and_b32_e32 v73, 0xffff0000, v51
	v_lshlrev_b32_e32 v72, 16, v51
	s_mov_b64 s[28:29], 0
	s_mov_b64 s[92:93], -1
	v_lshlrev_b32_e32 v152, 1, v64
	v_or_b32_e32 v126, v222, v65
	v_lshlrev_b32_e32 v126, 1, v126
	v_lshlrev_b32_e32 v127, 2, v223
	v_mov_b32_e32 v122, v66
	v_mov_b32_e32 v123, v153
	v_lshl_add_u64 v[122:123], v[68:69], 0, v[122:123]
	v_mov_b32_e32 v124, v127
	v_mov_b32_e32 v125, v153
	v_lshl_add_u64 v[124:125], v[122:123], 0, v[124:125]
	v_lshlrev_b64 v[124:125], 11, v[124:125]
	v_or_b32_e32 v124, v124, v126
	v_lshl_add_u64 v[124:125], s[10:11], 0, v[124:125]
	global_load_ushort v114, v[124:125], off offset:1536
	global_load_ushort v115, v[124:125], off offset:1600
	v_or_b32_e32 v124, 1, v127
	v_mov_b32_e32 v125, v153
	v_lshl_add_u64 v[124:125], v[122:123], 0, v[124:125]
	v_lshlrev_b64 v[124:125], 11, v[124:125]
	v_or_b32_e32 v124, v124, v126
	v_lshl_add_u64 v[124:125], s[10:11], 0, v[124:125]
	global_load_ushort v116, v[124:125], off offset:1536
	global_load_ushort v117, v[124:125], off offset:1600
	v_or_b32_e32 v124, 2, v127
	v_mov_b32_e32 v125, v153
	v_lshl_add_u64 v[124:125], v[122:123], 0, v[124:125]
	v_lshlrev_b64 v[124:125], 11, v[124:125]
	v_or_b32_e32 v124, v124, v126
	v_lshl_add_u64 v[124:125], s[10:11], 0, v[124:125]
	global_load_ushort v118, v[124:125], off offset:1536
	global_load_ushort v119, v[124:125], off offset:1600
	v_or_b32_e32 v124, 3, v127
	v_mov_b32_e32 v125, v153
	v_lshl_add_u64 v[124:125], v[122:123], 0, v[124:125]
	v_lshlrev_b64 v[124:125], 11, v[124:125]
	v_or_b32_e32 v124, v124, v126
	v_lshl_add_u64 v[124:125], s[10:11], 0, v[124:125]
	global_load_ushort v120, v[124:125], off offset:1536
	global_load_ushort v121, v[124:125], off offset:1600
	v_or_b32_e32 v124, 8, v127
	v_mov_b32_e32 v125, v153
	v_lshl_add_u64 v[124:125], v[122:123], 0, v[124:125]
	v_lshlrev_b64 v[124:125], 11, v[124:125]
	v_or_b32_e32 v124, v124, v126
	v_lshl_add_u64 v[124:125], s[10:11], 0, v[124:125]
	global_load_ushort v128, v[124:125], off offset:1536
	global_load_ushort v129, v[124:125], off offset:1600
	v_or_b32_e32 v124, 9, v127
	v_mov_b32_e32 v125, v153
	v_lshl_add_u64 v[124:125], v[122:123], 0, v[124:125]
	v_lshlrev_b64 v[124:125], 11, v[124:125]
	v_or_b32_e32 v124, v124, v126
	v_lshl_add_u64 v[124:125], s[10:11], 0, v[124:125]
	global_load_ushort v130, v[124:125], off offset:1536
	global_load_ushort v131, v[124:125], off offset:1600
	v_or_b32_e32 v124, 10, v127
	v_mov_b32_e32 v125, v153
	v_lshl_add_u64 v[124:125], v[122:123], 0, v[124:125]
	v_lshlrev_b64 v[124:125], 11, v[124:125]
	v_or_b32_e32 v124, v124, v126
	v_lshl_add_u64 v[124:125], s[10:11], 0, v[124:125]
	global_load_ushort v132, v[124:125], off offset:1536
	global_load_ushort v133, v[124:125], off offset:1600
	v_or_b32_e32 v124, 11, v127
	v_mov_b32_e32 v125, v153
	v_lshl_add_u64 v[124:125], v[122:123], 0, v[124:125]
	v_lshlrev_b64 v[124:125], 11, v[124:125]
	v_or_b32_e32 v124, v124, v126
	v_lshl_add_u64 v[124:125], s[10:11], 0, v[124:125]
	global_load_ushort v134, v[124:125], off offset:1536
	global_load_ushort v135, v[124:125], off offset:1600
	v_or_b32_e32 v124, 16, v127
	v_mov_b32_e32 v125, v153
	v_lshl_add_u64 v[124:125], v[122:123], 0, v[124:125]
	v_lshlrev_b64 v[124:125], 11, v[124:125]
	v_or_b32_e32 v124, v124, v126
	v_lshl_add_u64 v[124:125], s[10:11], 0, v[124:125]
	global_load_ushort v136, v[124:125], off offset:1536
	global_load_ushort v137, v[124:125], off offset:1600
	v_or_b32_e32 v124, 17, v127
	v_mov_b32_e32 v125, v153
	v_lshl_add_u64 v[124:125], v[122:123], 0, v[124:125]
	v_lshlrev_b64 v[124:125], 11, v[124:125]
	v_or_b32_e32 v124, v124, v126
	v_lshl_add_u64 v[124:125], s[10:11], 0, v[124:125]
	global_load_ushort v138, v[124:125], off offset:1536
	global_load_ushort v139, v[124:125], off offset:1600
	v_or_b32_e32 v124, 18, v127
	v_mov_b32_e32 v125, v153
	v_lshl_add_u64 v[124:125], v[122:123], 0, v[124:125]
	v_lshlrev_b64 v[124:125], 11, v[124:125]
	v_or_b32_e32 v124, v124, v126
; __device__ __forceinline__ unsigned pk2(float lo, float hi) { return pg8::pk_bf16_rne(lo, hi); }
; __device__ __forceinline__ float bf2f(unsigned short u) { return __uint_as_float(((unsigned)u) << 16); }
; __device__ __forceinline__ int crow(int r, int hi) { return (r & 3) + 8 * (r >> 2) + 4 * hi; }
; #define MFMA32(a, b, c) __builtin_amdgcn_mfma_f32_32x32x16_bf16((a), (b), (c), 0, 0, 0)
; __device__ __forceinline__ void ret_out(const Params& P, int l, unsigned char* lds, int u, int tid) {
;     ...
;     for (int dir = 0; dir < 2; ++dir) {
;         const bf16_t* Rt = RT + ((size_t)unit * 2 + dir) * 4096;
;         const float wq = dir == 0 ? __builtin_amdgcn_exp2f(lgf2 * (float)(cq + 1)) : __builtin_amdgcn_exp2f(lgb2 * (float)(128 - cq));
; #pragma unroll
;         for (int s = 0; s < 4; ++s) {
;             u32x4 w;
; #pragma unroll
;             for (int j = 0; j < 4; ++j) w[j] = pk2(bf2f((unsigned short)qr[s][2 * j]) * wq, bf2f((unsigned short)qr[s][2 * j + 1]) * wq);
;             const bf16x8 A = __builtin_bit_cast(bf16x8, w);
;             const bf16x8 b0 = *(const bf16x8*)(Rt + r32 * 64 + 16 * s + 8 * hi), b1 = *(const bf16x8*)(Rt + (32 + r32) * 64 + 16 * s + 8 * hi);
;             o0 = MFMA32(A, b0, o0); o1 = MFMA32(A, b1, o1);
;         }
;     ...
;         const size_t t = tc + c0f + crow(r, hi);
;         const float ga = bf2f(ZR[t * 1024 + 768 + h * 64 + r32]), gb = bf2f(ZR[t * 1024 + 768 + h * 64 + 32 + r32]);
	v_lshl_add_u64 v[124:125], s[10:11], 0, v[124:125]
	global_load_ushort v140, v[124:125], off offset:1536
	global_load_ushort v141, v[124:125], off offset:1600
	v_or_b32_e32 v124, 19, v127
	v_mov_b32_e32 v125, v153
	v_lshl_add_u64 v[124:125], v[122:123], 0, v[124:125]
	v_lshlrev_b64 v[124:125], 11, v[124:125]
	v_or_b32_e32 v124, v124, v126
	v_lshl_add_u64 v[124:125], s[10:11], 0, v[124:125]
	global_load_ushort v142, v[124:125], off offset:1536
	global_load_ushort v143, v[124:125], off offset:1600
	v_or_b32_e32 v124, 24, v127
	v_mov_b32_e32 v125, v153
	v_lshl_add_u64 v[124:125], v[122:123], 0, v[124:125]
	v_lshlrev_b64 v[124:125], 11, v[124:125]
	v_or_b32_e32 v124, v124, v126
	v_lshl_add_u64 v[124:125], s[10:11], 0, v[124:125]
	global_load_ushort v144, v[124:125], off offset:1536
	global_load_ushort v145, v[124:125], off offset:1600
	v_or_b32_e32 v124, 25, v127
	v_mov_b32_e32 v125, v153
	v_lshl_add_u64 v[124:125], v[122:123], 0, v[124:125]
	v_lshlrev_b64 v[124:125], 11, v[124:125]
	v_or_b32_e32 v124, v124, v126
	v_lshl_add_u64 v[124:125], s[10:11], 0, v[124:125]
	global_load_ushort v146, v[124:125], off offset:1536
	global_load_ushort v147, v[124:125], off offset:1600
	v_or_b32_e32 v124, 26, v127
	v_mov_b32_e32 v125, v153
	v_lshl_add_u64 v[124:125], v[122:123], 0, v[124:125]
	v_lshlrev_b64 v[124:125], 11, v[124:125]
	v_or_b32_e32 v124, v124, v126
	v_lshl_add_u64 v[124:125], s[10:11], 0, v[124:125]
	global_load_ushort v148, v[124:125], off offset:1536
	global_load_ushort v149, v[124:125], off offset:1600
	v_or_b32_e32 v124, 27, v127
	v_mov_b32_e32 v125, v153
	v_lshl_add_u64 v[124:125], v[122:123], 0, v[124:125]
	v_lshlrev_b64 v[124:125], 11, v[124:125]
	v_or_b32_e32 v124, v124, v126
	v_lshl_add_u64 v[124:125], s[10:11], 0, v[124:125]
	global_load_ushort v150, v[124:125], off offset:1536
	global_load_ushort v151, v[124:125], off offset:1600
.LBB0_145:
	v_lshl_add_u64 v[50:51], s[28:29], 1, v[32:33]
	v_cndmask_b32_e64 v64, v67, v74, s[92:93]
	v_lshl_add_u64 v[88:89], v[50:51], 0, v[152:153]
	v_pk_mul_f32 v[76:77], v[64:65], v[34:35] op_sel_hi:[0,1]
	v_pk_mul_f32 v[78:79], v[64:65], v[36:37] op_sel_hi:[0,1]
	v_add_co_u32_e32 v84, vcc, s36, v88
	v_cvt_pk_bf16_f32 v76, v76, v77
	v_cvt_pk_bf16_f32 v77, v78, v79
	v_pk_mul_f32 v[78:79], v[64:65], v[38:39] op_sel_hi:[0,1]
	v_pk_mul_f32 v[80:81], v[64:65], v[40:41] op_sel_hi:[0,1]
	v_addc_co_u32_e32 v85, vcc, 0, v89, vcc
	v_cvt_pk_bf16_f32 v78, v78, v79
	v_cvt_pk_bf16_f32 v79, v80, v81
	global_load_dwordx4 v[80:83], v[88:89], off
	s_mov_b64 s[28:29], 0x1000
	global_load_dwordx4 v[84:87], v[84:85], off
	v_lshl_add_u64 v[50:51], v[88:89], 0, s[28:29]
	global_load_dwordx4 v[90:93], v[88:89], off offset:32
	global_load_dwordx4 v[94:97], v[50:51], off offset:32
	global_load_dwordx4 v[98:101], v[88:89], off offset:64
	global_load_dwordx4 v[102:105], v[50:51], off offset:64
	global_load_dwordx4 v[106:109], v[88:89], off offset:96
	global_load_dwordx4 v[110:113], v[50:51], off offset:96
	s_and_b64 vcc, exec, s[92:93]
	s_mov_b64 s[92:93], 0
	s_waitcnt vmcnt(7)
	v_mfma_f32_32x32x16_bf16 v[0:15], v[76:79], v[80:83], v[0:15]
	v_mul_f32_e64 v80, v64, v56
	v_mul_f32_e64 v81, v64, v57
	s_waitcnt vmcnt(6)
	v_mfma_f32_32x32x16_bf16 v[16:31], v[76:79], v[84:87], v[16:31]
	v_mul_f32_e64 v76, v64, v42
	v_mul_f32_e64 v77, v64, v43
	v_mul_f32_e64 v78, v64, v44
	v_mul_f32_e64 v79, v64, v45
	v_cvt_pk_bf16_f32 v76, v76, v77
	v_cvt_pk_bf16_f32 v77, v78, v79
	v_pk_mul_f32 v[78:79], v[64:65], v[46:47] op_sel_hi:[0,1]
	v_cvt_pk_bf16_f32 v78, v78, v79
	v_cvt_pk_bf16_f32 v79, v80, v81
	s_nop 0
	s_nop 0
	s_waitcnt vmcnt(5)
	v_mfma_f32_32x32x16_bf16 v[0:15], v[76:79], v[90:93], v[0:15]
	v_mul_f32_e64 v80, v64, v62
	v_mul_f32_e64 v81, v64, v63
	s_waitcnt vmcnt(4)
	v_mfma_f32_32x32x16_bf16 v[16:31], v[76:79], v[94:97], v[16:31]
	v_mul_f32_e64 v76, v64, v58
	v_mul_f32_e64 v77, v64, v59
	v_mul_f32_e64 v78, v64, v60
	v_mul_f32_e64 v79, v64, v61
	v_cvt_pk_bf16_f32 v76, v76, v77
	v_cvt_pk_bf16_f32 v77, v78, v79
	v_pk_mul_f32 v[78:79], v[64:65], v[52:53] op_sel_hi:[0,1]
	v_cvt_pk_bf16_f32 v78, v78, v79
	v_cvt_pk_bf16_f32 v79, v80, v81
	s_nop 0
	s_nop 0
	s_waitcnt vmcnt(3)
	v_mfma_f32_32x32x16_bf16 v[0:15], v[76:79], v[98:101], v[0:15]
	v_mul_f32_e64 v80, v64, v72
	v_mul_f32_e64 v81, v64, v73
	s_waitcnt vmcnt(2)
	v_mfma_f32_32x32x16_bf16 v[16:31], v[76:79], v[102:105], v[16:31]
	v_mul_f32_e64 v76, v64, v54
	v_mul_f32_e64 v77, v64, v55
	v_mul_f32_e64 v78, v64, v70
	v_mul_f32_e64 v79, v64, v71
	v_cvt_pk_bf16_f32 v76, v76, v77
	v_cvt_pk_bf16_f32 v77, v78, v79
	v_pk_mul_f32 v[78:79], v[64:65], v[48:49] op_sel_hi:[0,1]
	v_cvt_pk_bf16_f32 v78, v78, v79
	v_cvt_pk_bf16_f32 v79, v80, v81
	s_nop 0
	s_nop 0
	s_waitcnt vmcnt(1)
	v_mfma_f32_32x32x16_bf16 v[0:15], v[76:79], v[106:109], v[0:15]
	s_waitcnt vmcnt(0)
	v_mfma_f32_32x32x16_bf16 v[16:31], v[76:79], v[110:113], v[16:31]
	s_cbranch_vccnz .LBB0_145
; #define LAUNDER_V(x) asm volatile("" : "+v"(x))
; __device__ __forceinline__ unsigned pk2(float lo, float hi) { return pg8::pk_bf16_rne(lo, hi); }
; __device__ __forceinline__ float bf2f(unsigned short u) { return __uint_as_float(((unsigned)u) << 16); }
; __device__ __forceinline__ float half_sum(float v) { v = row16_allsum(v); v = rows_pair_sum(v); return v; }
; __device__ __forceinline__ int crow(int r, int hi) { return (r & 3) + 8 * (r >> 2) + 4 * hi; }
; __device__ __forceinline__ void ret_out(const Params& P, int l, unsigned char* lds, int u, int tid) {
;     ...
;     const float g0 = gn[h * 64 + r32], g1 = gn[h * 64 + 32 + r32];
;     int c0f = c0; LAUNDER_V(c0f);
; #pragma unroll
;     for (int r = 0; r < 16; ++r) {
;         const float mean = half_sum(o0[r] + o1[r]) * (1.0f / 64.0f);
;         const float d0 = o0[r] - mean, d1 = o1[r] - mean;
;         const float var = half_sum(d0 * d0 + d1 * d1) * (1.0f / 64.0f);
;         const float rstd = 1.0f / sqrtf(var + 1e-5f);
;         const size_t t = tc + c0f + crow(r, hi);
;         const float ga = bf2f(ZR[t * 1024 + 768 + h * 64 + r32]), gb = bf2f(ZR[t * 1024 + 768 + h * 64 + 32 + r32]);
;         const float sa = ga / (1.0f + __expf(-ga)), sb = gb / (1.0f + __expf(-gb));
;         MIX[t * 1024 + 768 + h * 64 + r32] = (bf16_t)(pk2(sa * d0 * rstd * g0, 0.f) & 0xffffu);
;         MIX[t * 1024 + 768 + h * 64 + 32 + r32] = (bf16_t)(pk2(sb * d1 * rstd * g1, 0.f) & 0xffffu);
;     }
	s_nop 10
	v_add_f32_e32 v34, v0, v16
	s_lshl_b32 s18, s88, 2
	s_add_u32 s18, s12, s18
	v_add_f32_dpp v34, v34, v34 row_ror:8 row_mask:0xf bank_mask:0xf bound_ctrl:1
	s_addc_u32 s19, s13, 0
	s_add_u32 s12, s6, 0x2c00000
	v_add_f32_dpp v34, v34, v34 row_ror:4 row_mask:0xf bank_mask:0xf bound_ctrl:1
	s_addc_u32 s13, s7, 0
	v_or_b32_e32 v36, v222, v65
	v_add_f32_dpp v34, v34, v34 row_ror:2 row_mask:0xf bank_mask:0xf bound_ctrl:1
	v_lshlrev_b32_e32 v32, 2, v36
	global_load_dword v39, v32, s[18:19]
	global_load_dword v38, v32, s[18:19] offset:128
	v_add_f32_dpp v34, v34, v34 row_ror:1 row_mask:0xf bank_mask:0xf bound_ctrl:1
	v_mov_b32_e32 v35, v34
	s_nop 1
	v_permlane16_swap_b32_e32 v34, v35
	v_add_f32_e32 v34, v34, v35
	v_fmamk_f32 v41, v34, 0xbc800000, v0
	v_fmamk_f32 v0, v34, 0xbc800000, v16
	v_mul_f32_e32 v16, v0, v0
	v_fmac_f32_e32 v16, v41, v41
	v_lshlrev_b32_e32 v152, 2, v223
	v_ashrrev_i32_e32 v67, 31, v66
	v_add_f32_dpp v16, v16, v16 row_ror:8 row_mask:0xf bank_mask:0xf bound_ctrl:1
	v_lshl_add_u64 v[32:33], v[68:69], 0, v[66:67]
	s_nop 0
	v_add_f32_dpp v16, v16, v16 row_ror:4 row_mask:0xf bank_mask:0xf bound_ctrl:1
	s_nop 1
	v_add_f32_dpp v16, v16, v16 row_ror:2 row_mask:0xf bank_mask:0xf bound_ctrl:1
	s_nop 1
	v_add_f32_dpp v16, v16, v16 row_ror:1 row_mask:0xf bank_mask:0xf bound_ctrl:1
	v_mov_b32_e32 v34, v16
	s_nop 1
	v_permlane16_swap_b32_e32 v16, v34
	v_add_f32_e32 v16, v16, v34
	v_fmamk_f32 v16, v16, 0x3c800000, v200
	v_cmp_gt_f32_e32 vcc, s43, v16
	v_mul_f32_e32 v34, 0x4f800000, v16
	s_nop 0
	v_cndmask_b32_e32 v16, v16, v34, vcc
	v_sqrt_f32_e32 v34, v16
	s_nop 0
	v_add_u32_e32 v35, -1, v34
	v_fma_f32 v37, -v35, v34, v16
	v_cmp_ge_f32_e64 s[6:7], 0, v37
	v_add_u32_e32 v37, 1, v34
	s_nop 0
	v_cndmask_b32_e64 v35, v34, v35, s[6:7]
	v_fma_f32 v34, -v37, v34, v16
	v_cmp_lt_f32_e64 s[6:7], 0, v34
	s_nop 1
	v_cndmask_b32_e64 v34, v35, v37, s[6:7]
	v_mul_f32_e32 v35, 0x37800000, v34
	v_cndmask_b32_e32 v34, v34, v35, vcc
	v_cmp_class_f32_e32 vcc, v16, v175
	s_nop 1
	v_cndmask_b32_e32 v16, v34, v16, vcc
	v_div_scale_f32 v34, s[6:7], v16, v16, 1.0
	v_rcp_f32_e32 v35, v34
	s_nop 0
	v_fma_f32 v37, -v34, v35, 1.0
	v_fmac_f32_e32 v35, v37, v35
	v_div_scale_f32 v37, vcc, 1.0, v16, 1.0
	v_mul_f32_e32 v40, v37, v35
	v_fma_f32 v42, -v34, v40, v37
	v_fmac_f32_e32 v40, v42, v35
	v_fma_f32 v34, -v34, v40, v37
	v_div_fmas_f32 v34, v34, v35, v40
	v_div_fixup_f32 v16, v34, v16, 1.0
	v_lshl_add_u64 v[34:35], v[32:33], 0, v[152:153]
	v_lshlrev_b64 v[34:35], 11, v[34:35]
	v_lshlrev_b32_e32 v40, 1, v36
	v_or_b32_e32 v42, v34, v40
	v_or_b32_e32 v34, 0x600, v42
	v_lshl_add_u64 v[36:37], s[10:11], 0, v[34:35]
	s_nop 0
	v_mov_b32_e32 v37, v35
	v_lshl_add_u64 v[34:35], s[12:13], 0, v[34:35]
	s_waitcnt vmcnt(0)
	v_lshlrev_b32_e32 v44, 16, v114
	v_or_b32_e32 v36, 0x640, v42
	v_lshl_add_u64 v[42:43], s[10:11], 0, v[36:37]
	s_nop 0
	v_mul_f32_e32 v43, 0xbfb8aa3b, v44
	v_exp_f32_e32 v43, v43
	v_lshlrev_b32_e32 v42, 16, v115
	v_add_f32_e32 v43, 1.0, v43
	v_div_scale_f32 v45, s[6:7], v43, v43, v44
	v_rcp_f32_e32 v46, v45
	s_nop 0
	v_fma_f32 v47, -v45, v46, 1.0
	v_fmac_f32_e32 v46, v47, v46
	v_div_scale_f32 v47, vcc, v44, v43, v44
	v_mul_f32_e32 v48, v47, v46
	v_fma_f32 v49, -v45, v48, v47
	v_fmac_f32_e32 v48, v49, v46
	v_fma_f32 v45, -v45, v48, v47
	v_div_fmas_f32 v45, v45, v46, v48
	v_div_fixup_f32 v43, v45, v43, v44
	v_mul_f32_e32 v44, 0xbfb8aa3b, v42
	v_exp_f32_e32 v44, v44
	v_mul_f32_e32 v41, v41, v43
	v_mul_f32_e32 v41, v16, v41
	v_mul_f32_e32 v41, v39, v41
	v_add_f32_e32 v44, 1.0, v44
	v_div_scale_f32 v45, s[6:7], v44, v44, v42
	v_rcp_f32_e32 v46, v45
	v_cvt_pk_bf16_f32 v41, v41, s0
	global_store_short v[34:35], v41, off
	v_lshl_add_u64 v[34:35], s[12:13], 0, v[36:37]
	v_fma_f32 v47, -v45, v46, 1.0
	v_fmac_f32_e32 v46, v47, v46
	v_div_scale_f32 v47, vcc, v42, v44, v42
	v_mul_f32_e32 v48, v47, v46
	v_fma_f32 v49, -v45, v48, v47
	v_fmac_f32_e32 v48, v49, v46
	v_fma_f32 v45, -v45, v48, v47
	v_div_fmas_f32 v45, v45, v46, v48
	v_div_fixup_f32 v42, v45, v44, v42
	v_mul_f32_e32 v0, v0, v42
	v_mul_f32_e32 v0, v16, v0
	v_mul_f32_e32 v0, v38, v0
	v_cvt_pk_bf16_f32 v0, v0, s0
	global_store_short v[34:35], v0, off
	v_add_f32_e32 v0, v1, v17
	s_nop 1
	v_add_f32_dpp v0, v0, v0 row_ror:8 row_mask:0xf bank_mask:0xf bound_ctrl:1
	s_nop 1
	v_add_f32_dpp v0, v0, v0 row_ror:4 row_mask:0xf bank_mask:0xf bound_ctrl:1
	s_nop 1
	v_add_f32_dpp v0, v0, v0 row_ror:2 row_mask:0xf bank_mask:0xf bound_ctrl:1
	s_nop 1
	v_add_f32_dpp v0, v0, v0 row_ror:1 row_mask:0xf bank_mask:0xf bound_ctrl:1
	v_mov_b32_e32 v16, v0
	s_nop 1
	v_permlane16_swap_b32_e32 v0, v16
	v_add_f32_e32 v0, v0, v16
	v_fmamk_f32 v34, v0, 0xbc800000, v17
	v_fmamk_f32 v35, v0, 0xbc800000, v1
	v_mul_f32_e32 v0, v34, v34
	v_fmac_f32_e32 v0, v35, v35
	s_nop 1
	v_add_f32_dpp v0, v0, v0 row_ror:8 row_mask:0xf bank_mask:0xf bound_ctrl:1
	s_nop 1
	v_add_f32_dpp v0, v0, v0 row_ror:4 row_mask:0xf bank_mask:0xf bound_ctrl:1
	s_nop 1
	v_add_f32_dpp v0, v0, v0 row_ror:2 row_mask:0xf bank_mask:0xf bound_ctrl:1
	s_nop 1
	v_add_f32_dpp v0, v0, v0 row_ror:1 row_mask:0xf bank_mask:0xf bound_ctrl:1
	v_mov_b32_e32 v1, v0
	s_nop 1
	v_permlane16_swap_b32_e32 v0, v1
	v_add_f32_e32 v0, v0, v1
	v_fmamk_f32 v0, v0, 0x3c800000, v200
	v_cmp_gt_f32_e32 vcc, s43, v0
	v_mul_f32_e32 v1, 0x4f800000, v0
	s_nop 0
	v_cndmask_b32_e32 v0, v0, v1, vcc
	v_sqrt_f32_e32 v1, v0
	s_nop 0
	v_add_u32_e32 v16, -1, v1
	v_fma_f32 v17, -v16, v1, v0
	v_cmp_ge_f32_e64 s[6:7], 0, v17
	v_add_u32_e32 v17, 1, v1
	s_nop 0
	v_cndmask_b32_e64 v16, v1, v16, s[6:7]
	v_fma_f32 v1, -v17, v1, v0
	v_cmp_lt_f32_e64 s[6:7], 0, v1
	s_nop 1
	v_cndmask_b32_e64 v1, v16, v17, s[6:7]
; __device__ __forceinline__ unsigned pk2(float lo, float hi) { return pg8::pk_bf16_rne(lo, hi); }
; __device__ __forceinline__ float bf2f(unsigned short u) { return __uint_as_float(((unsigned)u) << 16); }
; __device__ __forceinline__ float half_sum(float v) { v = row16_allsum(v); v = rows_pair_sum(v); return v; }
; __device__ __forceinline__ int crow(int r, int hi) { return (r & 3) + 8 * (r >> 2) + 4 * hi; }
; __device__ __forceinline__ void ret_out(const Params& P, int l, unsigned char* lds, int u, int tid) {
;     ...
;     for (int r = 0; r < 16; ++r) {
;         const float mean = half_sum(o0[r] + o1[r]) * (1.0f / 64.0f);
;         const float d0 = o0[r] - mean, d1 = o1[r] - mean;
;         const float var = half_sum(d0 * d0 + d1 * d1) * (1.0f / 64.0f);
;         const float rstd = 1.0f / sqrtf(var + 1e-5f);
;         const size_t t = tc + c0f + crow(r, hi);
;         const float ga = bf2f(ZR[t * 1024 + 768 + h * 64 + r32]), gb = bf2f(ZR[t * 1024 + 768 + h * 64 + 32 + r32]);
;         const float sa = ga / (1.0f + __expf(-ga)), sb = gb / (1.0f + __expf(-gb));
;         MIX[t * 1024 + 768 + h * 64 + r32] = (bf16_t)(pk2(sa * d0 * rstd * g0, 0.f) & 0xffffu);
;         MIX[t * 1024 + 768 + h * 64 + 32 + r32] = (bf16_t)(pk2(sb * d1 * rstd * g1, 0.f) & 0xffffu);
;     }
	v_mul_f32_e32 v16, 0x37800000, v1
	v_cndmask_b32_e32 v1, v1, v16, vcc
	v_cmp_class_f32_e32 vcc, v0, v175
	s_nop 1
	v_cndmask_b32_e32 v0, v1, v0, vcc
	v_div_scale_f32 v1, s[6:7], v0, v0, 1.0
	v_rcp_f32_e32 v16, v1
	s_nop 0
	v_fma_f32 v17, -v1, v16, 1.0
	v_fmac_f32_e32 v16, v17, v16
	v_div_scale_f32 v17, vcc, 1.0, v0, 1.0
	v_mul_f32_e32 v36, v17, v16
	v_fma_f32 v37, -v1, v36, v17
	v_fmac_f32_e32 v36, v37, v16
	v_fma_f32 v1, -v1, v36, v17
	v_div_fmas_f32 v1, v1, v16, v36
	v_div_fixup_f32 v36, v1, v0, 1.0
	v_or_b32_e32 v0, 1, v152
	v_mov_b32_e32 v1, v153
	v_lshl_add_u64 v[0:1], v[32:33], 0, v[0:1]
	v_lshlrev_b64 v[0:1], 11, v[0:1]
	v_or_b32_e32 v37, v0, v40
	v_or_b32_e32 v0, 0x600, v37
	v_lshl_add_u64 v[16:17], s[10:11], 0, v[0:1]
	s_nop 0
	v_mov_b32_e32 v17, v1
	v_lshl_add_u64 v[0:1], s[12:13], 0, v[0:1]
	v_lshlrev_b32_e32 v41, 16, v116
	v_or_b32_e32 v16, 0x640, v37
	v_lshl_add_u64 v[42:43], s[10:11], 0, v[16:17]
	s_nop 0
	v_mul_f32_e32 v42, 0xbfb8aa3b, v41
	v_exp_f32_e32 v42, v42
	v_lshlrev_b32_e32 v37, 16, v117
	v_add_f32_e32 v42, 1.0, v42
	v_div_scale_f32 v43, s[6:7], v42, v42, v41
	v_rcp_f32_e32 v44, v43
	s_nop 0
	v_fma_f32 v45, -v43, v44, 1.0
	v_fmac_f32_e32 v44, v45, v44
	v_div_scale_f32 v45, vcc, v41, v42, v41
	v_mul_f32_e32 v46, v45, v44
	v_fma_f32 v47, -v43, v46, v45
	v_fmac_f32_e32 v46, v47, v44
	v_fma_f32 v43, -v43, v46, v45
	v_div_fmas_f32 v43, v43, v44, v46
	v_div_fixup_f32 v41, v43, v42, v41
	v_mul_f32_e32 v42, 0xbfb8aa3b, v37
	v_exp_f32_e32 v42, v42
	v_mul_f32_e32 v35, v35, v41
	v_mul_f32_e32 v35, v36, v35
	v_mul_f32_e32 v35, v39, v35
	v_add_f32_e32 v42, 1.0, v42
	v_div_scale_f32 v43, s[6:7], v42, v42, v37
	v_rcp_f32_e32 v44, v43
	v_cvt_pk_bf16_f32 v35, v35, s0
	global_store_short v[0:1], v35, off
	v_fma_f32 v45, -v43, v44, 1.0
	v_fmac_f32_e32 v44, v45, v44
	v_div_scale_f32 v45, vcc, v37, v42, v37
	v_mul_f32_e32 v46, v45, v44
	v_fma_f32 v47, -v43, v46, v45
	v_fmac_f32_e32 v46, v47, v44
	v_fma_f32 v43, -v43, v46, v45
	v_div_fmas_f32 v43, v43, v44, v46
	v_div_fixup_f32 v37, v43, v42, v37
	v_mul_f32_e32 v0, v34, v37
	v_mul_f32_e32 v0, v36, v0
	v_mul_f32_e32 v0, v38, v0
	v_cvt_pk_bf16_f32 v34, v0, s0
	v_lshl_add_u64 v[0:1], s[12:13], 0, v[16:17]
	global_store_short v[0:1], v34, off
	v_add_f32_e32 v0, v2, v18
	s_nop 1
	v_add_f32_dpp v0, v0, v0 row_ror:8 row_mask:0xf bank_mask:0xf bound_ctrl:1
	s_nop 1
	v_add_f32_dpp v0, v0, v0 row_ror:4 row_mask:0xf bank_mask:0xf bound_ctrl:1
	s_nop 1
	v_add_f32_dpp v0, v0, v0 row_ror:2 row_mask:0xf bank_mask:0xf bound_ctrl:1
	s_nop 1
	v_add_f32_dpp v0, v0, v0 row_ror:1 row_mask:0xf bank_mask:0xf bound_ctrl:1
	v_mov_b32_e32 v1, v0
	s_nop 1
	v_permlane16_swap_b32_e32 v0, v1
	v_add_f32_e32 v0, v0, v1
	v_fmamk_f32 v34, v0, 0xbc800000, v2
	v_fmamk_f32 v2, v0, 0xbc800000, v18
	v_mul_f32_e32 v0, v2, v2
	v_fmac_f32_e32 v0, v34, v34
	s_nop 1
	v_add_f32_dpp v0, v0, v0 row_ror:8 row_mask:0xf bank_mask:0xf bound_ctrl:1
	s_nop 1
	v_add_f32_dpp v0, v0, v0 row_ror:4 row_mask:0xf bank_mask:0xf bound_ctrl:1
	s_nop 1
	v_add_f32_dpp v0, v0, v0 row_ror:2 row_mask:0xf bank_mask:0xf bound_ctrl:1
	s_nop 1
	v_add_f32_dpp v0, v0, v0 row_ror:1 row_mask:0xf bank_mask:0xf bound_ctrl:1
	v_mov_b32_e32 v1, v0
	s_nop 1
	v_permlane16_swap_b32_e32 v0, v1
	v_add_f32_e32 v0, v0, v1
	v_fmamk_f32 v0, v0, 0x3c800000, v200
	v_cmp_gt_f32_e32 vcc, s43, v0
	v_mul_f32_e32 v1, 0x4f800000, v0
	s_nop 0
	v_cndmask_b32_e32 v0, v0, v1, vcc
	v_sqrt_f32_e32 v1, v0
	s_nop 0
	v_add_u32_e32 v16, -1, v1
	v_fma_f32 v17, -v16, v1, v0
	v_cmp_ge_f32_e64 s[6:7], 0, v17
	v_add_u32_e32 v17, 1, v1
	s_nop 0
	v_cndmask_b32_e64 v16, v1, v16, s[6:7]
	v_fma_f32 v1, -v17, v1, v0
	v_cmp_lt_f32_e64 s[6:7], 0, v1
	s_nop 1
	v_cndmask_b32_e64 v1, v16, v17, s[6:7]
	v_mul_f32_e32 v16, 0x37800000, v1
	v_cndmask_b32_e32 v1, v1, v16, vcc
	v_cmp_class_f32_e32 vcc, v0, v175
	s_nop 1
	v_cndmask_b32_e32 v0, v1, v0, vcc
	v_div_scale_f32 v1, s[6:7], v0, v0, 1.0
	v_rcp_f32_e32 v16, v1
	s_nop 0
	v_fma_f32 v17, -v1, v16, 1.0
	v_fmac_f32_e32 v16, v17, v16
	v_div_scale_f32 v17, vcc, 1.0, v0, 1.0
	v_mul_f32_e32 v18, v17, v16
	v_fma_f32 v35, -v1, v18, v17
	v_fmac_f32_e32 v18, v35, v16
	v_fma_f32 v1, -v1, v18, v17
	v_div_fmas_f32 v1, v1, v16, v18
	v_div_fixup_f32 v18, v1, v0, 1.0
	v_or_b32_e32 v0, 2, v152
	v_mov_b32_e32 v1, v153
	v_lshl_add_u64 v[0:1], v[32:33], 0, v[0:1]
	v_lshlrev_b64 v[0:1], 11, v[0:1]
	v_or_b32_e32 v35, v0, v40
	v_or_b32_e32 v0, 0x600, v35
	v_lshl_add_u64 v[16:17], s[10:11], 0, v[0:1]
	s_nop 0
	v_mov_b32_e32 v17, v1
	v_lshl_add_u64 v[0:1], s[12:13], 0, v[0:1]
	v_lshlrev_b32_e32 v41, 16, v118
	v_or_b32_e32 v16, 0x640, v35
	v_lshl_add_u64 v[36:37], s[10:11], 0, v[16:17]
	s_nop 0
	v_mul_f32_e32 v36, 0xbfb8aa3b, v41
	v_exp_f32_e32 v36, v36
	v_lshlrev_b32_e32 v35, 16, v119
	v_add_f32_e32 v36, 1.0, v36
	v_div_scale_f32 v37, s[6:7], v36, v36, v41
	v_rcp_f32_e32 v42, v37
	s_nop 0
	v_fma_f32 v43, -v37, v42, 1.0
	v_fmac_f32_e32 v42, v43, v42
	v_div_scale_f32 v43, vcc, v41, v36, v41
	v_mul_f32_e32 v44, v43, v42
	v_fma_f32 v45, -v37, v44, v43
	v_fmac_f32_e32 v44, v45, v42
	v_fma_f32 v37, -v37, v44, v43
	v_div_fmas_f32 v37, v37, v42, v44
	v_div_fixup_f32 v36, v37, v36, v41
	v_mul_f32_e32 v37, 0xbfb8aa3b, v35
	v_exp_f32_e32 v37, v37
	v_mul_f32_e32 v34, v34, v36
	v_mul_f32_e32 v34, v18, v34
	v_mul_f32_e32 v34, v39, v34
	v_add_f32_e32 v37, 1.0, v37
	v_div_scale_f32 v41, s[6:7], v37, v37, v35
	v_rcp_f32_e32 v42, v41
	v_cvt_pk_bf16_f32 v34, v34, s0
	global_store_short v[0:1], v34, off
	v_fma_f32 v43, -v41, v42, 1.0
	v_fmac_f32_e32 v42, v43, v42
	v_div_scale_f32 v43, vcc, v35, v37, v35
	v_mul_f32_e32 v44, v43, v42
	v_fma_f32 v45, -v41, v44, v43
	v_fmac_f32_e32 v44, v45, v42
; __device__ __forceinline__ unsigned pk2(float lo, float hi) { return pg8::pk_bf16_rne(lo, hi); }
; __device__ __forceinline__ float bf2f(unsigned short u) { return __uint_as_float(((unsigned)u) << 16); }
; __device__ __forceinline__ float half_sum(float v) { v = row16_allsum(v); v = rows_pair_sum(v); return v; }
; __device__ __forceinline__ int crow(int r, int hi) { return (r & 3) + 8 * (r >> 2) + 4 * hi; }
; __device__ __forceinline__ void ret_out(const Params& P, int l, unsigned char* lds, int u, int tid) {
;     ...
;     for (int r = 0; r < 16; ++r) {
;         const float mean = half_sum(o0[r] + o1[r]) * (1.0f / 64.0f);
;         const float d0 = o0[r] - mean, d1 = o1[r] - mean;
;         const float var = half_sum(d0 * d0 + d1 * d1) * (1.0f / 64.0f);
;         const float rstd = 1.0f / sqrtf(var + 1e-5f);
;         const size_t t = tc + c0f + crow(r, hi);
;         const float ga = bf2f(ZR[t * 1024 + 768 + h * 64 + r32]), gb = bf2f(ZR[t * 1024 + 768 + h * 64 + 32 + r32]);
;         const float sa = ga / (1.0f + __expf(-ga)), sb = gb / (1.0f + __expf(-gb));
;         MIX[t * 1024 + 768 + h * 64 + r32] = (bf16_t)(pk2(sa * d0 * rstd * g0, 0.f) & 0xffffu);
;         MIX[t * 1024 + 768 + h * 64 + 32 + r32] = (bf16_t)(pk2(sb * d1 * rstd * g1, 0.f) & 0xffffu);
;     }
	v_fma_f32 v41, -v41, v44, v43
	v_div_fmas_f32 v41, v41, v42, v44
	v_div_fixup_f32 v35, v41, v37, v35
	v_mul_f32_e32 v0, v2, v35
	v_mul_f32_e32 v0, v18, v0
	v_mul_f32_e32 v0, v38, v0
	v_cvt_pk_bf16_f32 v2, v0, s0
	v_lshl_add_u64 v[0:1], s[12:13], 0, v[16:17]
	global_store_short v[0:1], v2, off
	v_add_f32_e32 v0, v3, v19
	s_nop 1
	v_add_f32_dpp v0, v0, v0 row_ror:8 row_mask:0xf bank_mask:0xf bound_ctrl:1
	s_nop 1
	v_add_f32_dpp v0, v0, v0 row_ror:4 row_mask:0xf bank_mask:0xf bound_ctrl:1
	s_nop 1
	v_add_f32_dpp v0, v0, v0 row_ror:2 row_mask:0xf bank_mask:0xf bound_ctrl:1
	s_nop 1
	v_add_f32_dpp v0, v0, v0 row_ror:1 row_mask:0xf bank_mask:0xf bound_ctrl:1
	v_mov_b32_e32 v1, v0
	s_nop 1
	v_permlane16_swap_b32_e32 v0, v1
	v_add_f32_e32 v0, v0, v1
	v_fmamk_f32 v16, v0, 0xbc800000, v19
	v_fmamk_f32 v17, v0, 0xbc800000, v3
	v_mul_f32_e32 v0, v16, v16
	v_fmac_f32_e32 v0, v17, v17
	s_nop 1
	v_add_f32_dpp v0, v0, v0 row_ror:8 row_mask:0xf bank_mask:0xf bound_ctrl:1
	s_nop 1
	v_add_f32_dpp v0, v0, v0 row_ror:4 row_mask:0xf bank_mask:0xf bound_ctrl:1
	s_nop 1
	v_add_f32_dpp v0, v0, v0 row_ror:2 row_mask:0xf bank_mask:0xf bound_ctrl:1
	s_nop 1
	v_add_f32_dpp v0, v0, v0 row_ror:1 row_mask:0xf bank_mask:0xf bound_ctrl:1
	v_mov_b32_e32 v1, v0
	s_nop 1
	v_permlane16_swap_b32_e32 v0, v1
	v_add_f32_e32 v0, v0, v1
	v_fmamk_f32 v0, v0, 0x3c800000, v200
	v_cmp_gt_f32_e32 vcc, s43, v0
	v_mul_f32_e32 v1, 0x4f800000, v0
	s_nop 0
	v_cndmask_b32_e32 v0, v0, v1, vcc
	v_sqrt_f32_e32 v1, v0
	s_nop 0
	v_add_u32_e32 v2, -1, v1
	v_fma_f32 v3, -v2, v1, v0
	v_cmp_ge_f32_e64 s[6:7], 0, v3
	v_add_u32_e32 v3, 1, v1
	s_nop 0
	v_cndmask_b32_e64 v2, v1, v2, s[6:7]
	v_fma_f32 v1, -v3, v1, v0
	v_cmp_lt_f32_e64 s[6:7], 0, v1
	s_nop 1
	v_cndmask_b32_e64 v1, v2, v3, s[6:7]
	v_mul_f32_e32 v2, 0x37800000, v1
	v_cndmask_b32_e32 v1, v1, v2, vcc
	v_cmp_class_f32_e32 vcc, v0, v175
	s_nop 1
	v_cndmask_b32_e32 v0, v1, v0, vcc
	v_div_scale_f32 v1, s[6:7], v0, v0, 1.0
	v_rcp_f32_e32 v2, v1
	s_nop 0
	v_fma_f32 v3, -v1, v2, 1.0
	v_fmac_f32_e32 v2, v3, v2
	v_div_scale_f32 v3, vcc, 1.0, v0, 1.0
	v_mul_f32_e32 v18, v3, v2
	v_fma_f32 v19, -v1, v18, v3
	v_fmac_f32_e32 v18, v19, v2
	v_fma_f32 v1, -v1, v18, v3
	v_div_fmas_f32 v1, v1, v2, v18
	v_div_fixup_f32 v18, v1, v0, 1.0
	v_or_b32_e32 v0, 3, v152
	v_mov_b32_e32 v1, v153
	v_lshl_add_u64 v[0:1], v[32:33], 0, v[0:1]
	v_lshlrev_b64 v[0:1], 11, v[0:1]
	v_or_b32_e32 v19, v0, v40
	v_or_b32_e32 v0, 0x600, v19
	v_lshl_add_u64 v[2:3], s[10:11], 0, v[0:1]
	s_nop 0
	v_mov_b32_e32 v3, v1
	v_lshl_add_u64 v[0:1], s[12:13], 0, v[0:1]
	v_lshlrev_b32_e32 v36, 16, v120
	v_or_b32_e32 v2, 0x640, v19
	v_lshl_add_u64 v[34:35], s[10:11], 0, v[2:3]
	s_nop 0
	v_mul_f32_e32 v34, 0xbfb8aa3b, v36
	v_exp_f32_e32 v34, v34
	v_lshlrev_b32_e32 v19, 16, v121
	v_add_f32_e32 v34, 1.0, v34
	v_div_scale_f32 v35, s[6:7], v34, v34, v36
	v_rcp_f32_e32 v37, v35
	s_nop 0
	v_fma_f32 v41, -v35, v37, 1.0
	v_fmac_f32_e32 v37, v41, v37
	v_div_scale_f32 v41, vcc, v36, v34, v36
	v_mul_f32_e32 v42, v41, v37
	v_fma_f32 v43, -v35, v42, v41
	v_fmac_f32_e32 v42, v43, v37
	v_fma_f32 v35, -v35, v42, v41
	v_div_fmas_f32 v35, v35, v37, v42
	v_div_fixup_f32 v34, v35, v34, v36
	v_mul_f32_e32 v35, 0xbfb8aa3b, v19
	v_exp_f32_e32 v35, v35
	v_mul_f32_e32 v17, v17, v34
	v_mul_f32_e32 v17, v18, v17
	v_mul_f32_e32 v17, v39, v17
	v_add_f32_e32 v35, 1.0, v35
	v_div_scale_f32 v36, s[6:7], v35, v35, v19
	v_rcp_f32_e32 v37, v36
	v_cvt_pk_bf16_f32 v17, v17, s0
	global_store_short v[0:1], v17, off
	v_fma_f32 v41, -v36, v37, 1.0
	v_fmac_f32_e32 v37, v41, v37
	v_div_scale_f32 v41, vcc, v19, v35, v19
	v_mul_f32_e32 v42, v41, v37
	v_fma_f32 v43, -v36, v42, v41
	v_fmac_f32_e32 v42, v43, v37
	v_fma_f32 v36, -v36, v42, v41
	v_div_fmas_f32 v36, v36, v37, v42
	v_div_fixup_f32 v19, v36, v35, v19
	v_mul_f32_e32 v0, v16, v19
	v_mul_f32_e32 v0, v18, v0
	v_mul_f32_e32 v0, v38, v0
	v_cvt_pk_bf16_f32 v16, v0, s0
	v_lshl_add_u64 v[0:1], s[12:13], 0, v[2:3]
	global_store_short v[0:1], v16, off
	v_add_f32_e32 v0, v4, v20
	s_nop 1
	v_add_f32_dpp v0, v0, v0 row_ror:8 row_mask:0xf bank_mask:0xf bound_ctrl:1
	s_nop 1
	v_add_f32_dpp v0, v0, v0 row_ror:4 row_mask:0xf bank_mask:0xf bound_ctrl:1
	s_nop 1
	v_add_f32_dpp v0, v0, v0 row_ror:2 row_mask:0xf bank_mask:0xf bound_ctrl:1
	s_nop 1
	v_add_f32_dpp v0, v0, v0 row_ror:1 row_mask:0xf bank_mask:0xf bound_ctrl:1
	v_mov_b32_e32 v1, v0
	s_nop 1
	v_permlane16_swap_b32_e32 v0, v1
	v_add_f32_e32 v0, v0, v1
	v_fmamk_f32 v16, v0, 0xbc800000, v4
	v_fmamk_f32 v4, v0, 0xbc800000, v20
	v_mul_f32_e32 v0, v4, v4
	v_fmac_f32_e32 v0, v16, v16
	s_nop 1
	v_add_f32_dpp v0, v0, v0 row_ror:8 row_mask:0xf bank_mask:0xf bound_ctrl:1
	s_nop 1
	v_add_f32_dpp v0, v0, v0 row_ror:4 row_mask:0xf bank_mask:0xf bound_ctrl:1
	s_nop 1
	v_add_f32_dpp v0, v0, v0 row_ror:2 row_mask:0xf bank_mask:0xf bound_ctrl:1
	s_nop 1
	v_add_f32_dpp v0, v0, v0 row_ror:1 row_mask:0xf bank_mask:0xf bound_ctrl:1
	v_mov_b32_e32 v1, v0
	s_nop 1
	v_permlane16_swap_b32_e32 v0, v1
	v_add_f32_e32 v0, v0, v1
	v_fmamk_f32 v0, v0, 0x3c800000, v200
	v_cmp_gt_f32_e32 vcc, s43, v0
	v_mul_f32_e32 v1, 0x4f800000, v0
	s_nop 0
	v_cndmask_b32_e32 v0, v0, v1, vcc
	v_sqrt_f32_e32 v1, v0
	s_nop 0
	v_add_u32_e32 v2, -1, v1
	v_fma_f32 v3, -v2, v1, v0
	v_cmp_ge_f32_e64 s[6:7], 0, v3
	v_add_u32_e32 v3, 1, v1
	s_nop 0
	v_cndmask_b32_e64 v2, v1, v2, s[6:7]
	v_fma_f32 v1, -v3, v1, v0
	v_cmp_lt_f32_e64 s[6:7], 0, v1
	s_nop 1
	v_cndmask_b32_e64 v1, v2, v3, s[6:7]
	v_mul_f32_e32 v2, 0x37800000, v1
	v_cndmask_b32_e32 v1, v1, v2, vcc
	v_cmp_class_f32_e32 vcc, v0, v175
	s_nop 1
	v_cndmask_b32_e32 v0, v1, v0, vcc
	v_div_scale_f32 v1, s[6:7], v0, v0, 1.0
	v_rcp_f32_e32 v2, v1
; __device__ __forceinline__ unsigned pk2(float lo, float hi) { return pg8::pk_bf16_rne(lo, hi); }
; __device__ __forceinline__ float bf2f(unsigned short u) { return __uint_as_float(((unsigned)u) << 16); }
; __device__ __forceinline__ float half_sum(float v) { v = row16_allsum(v); v = rows_pair_sum(v); return v; }
; __device__ __forceinline__ int crow(int r, int hi) { return (r & 3) + 8 * (r >> 2) + 4 * hi; }
; __device__ __forceinline__ void ret_out(const Params& P, int l, unsigned char* lds, int u, int tid) {
;     ...
;     for (int r = 0; r < 16; ++r) {
;         const float mean = half_sum(o0[r] + o1[r]) * (1.0f / 64.0f);
;         const float d0 = o0[r] - mean, d1 = o1[r] - mean;
;         const float var = half_sum(d0 * d0 + d1 * d1) * (1.0f / 64.0f);
;         const float rstd = 1.0f / sqrtf(var + 1e-5f);
;         const size_t t = tc + c0f + crow(r, hi);
;         const float ga = bf2f(ZR[t * 1024 + 768 + h * 64 + r32]), gb = bf2f(ZR[t * 1024 + 768 + h * 64 + 32 + r32]);
;         const float sa = ga / (1.0f + __expf(-ga)), sb = gb / (1.0f + __expf(-gb));
;         MIX[t * 1024 + 768 + h * 64 + r32] = (bf16_t)(pk2(sa * d0 * rstd * g0, 0.f) & 0xffffu);
;         MIX[t * 1024 + 768 + h * 64 + 32 + r32] = (bf16_t)(pk2(sb * d1 * rstd * g1, 0.f) & 0xffffu);
;     }
	s_nop 0
	v_fma_f32 v3, -v1, v2, 1.0
	v_fmac_f32_e32 v2, v3, v2
	v_div_scale_f32 v3, vcc, 1.0, v0, 1.0
	v_mul_f32_e32 v17, v3, v2
	v_fma_f32 v18, -v1, v17, v3
	v_fmac_f32_e32 v17, v18, v2
	v_fma_f32 v1, -v1, v17, v3
	v_div_fmas_f32 v1, v1, v2, v17
	v_div_fixup_f32 v17, v1, v0, 1.0
	v_or_b32_e32 v0, 8, v152
	v_mov_b32_e32 v1, v153
	v_lshl_add_u64 v[0:1], v[32:33], 0, v[0:1]
	v_lshlrev_b64 v[0:1], 11, v[0:1]
	v_or_b32_e32 v18, v0, v40
	v_or_b32_e32 v0, 0x600, v18
	v_lshl_add_u64 v[2:3], s[10:11], 0, v[0:1]
	s_nop 0
	v_mov_b32_e32 v3, v1
	v_lshl_add_u64 v[0:1], s[12:13], 0, v[0:1]
	v_lshlrev_b32_e32 v20, 16, v128
	v_or_b32_e32 v2, 0x640, v18
	v_lshl_add_u64 v[18:19], s[10:11], 0, v[2:3]
	s_nop 0
	v_mul_f32_e32 v19, 0xbfb8aa3b, v20
	v_exp_f32_e32 v19, v19
	v_lshlrev_b32_e32 v18, 16, v129
	v_add_f32_e32 v19, 1.0, v19
	v_div_scale_f32 v34, s[6:7], v19, v19, v20
	v_rcp_f32_e32 v35, v34
	s_nop 0
	v_fma_f32 v36, -v34, v35, 1.0
	v_fmac_f32_e32 v35, v36, v35
	v_div_scale_f32 v36, vcc, v20, v19, v20
	v_mul_f32_e32 v37, v36, v35
	v_fma_f32 v41, -v34, v37, v36
	v_fmac_f32_e32 v37, v41, v35
	v_fma_f32 v34, -v34, v37, v36
	v_div_fmas_f32 v34, v34, v35, v37
	v_div_fixup_f32 v19, v34, v19, v20
	v_mul_f32_e32 v20, 0xbfb8aa3b, v18
	v_exp_f32_e32 v20, v20
	v_mul_f32_e32 v16, v16, v19
	v_mul_f32_e32 v16, v17, v16
	v_mul_f32_e32 v16, v39, v16
	v_add_f32_e32 v20, 1.0, v20
	v_div_scale_f32 v34, s[6:7], v20, v20, v18
	v_rcp_f32_e32 v35, v34
	v_cvt_pk_bf16_f32 v16, v16, s0
	global_store_short v[0:1], v16, off
	v_fma_f32 v36, -v34, v35, 1.0
	v_fmac_f32_e32 v35, v36, v35
	v_div_scale_f32 v36, vcc, v18, v20, v18
	v_mul_f32_e32 v37, v36, v35
	v_fma_f32 v41, -v34, v37, v36
	v_fmac_f32_e32 v37, v41, v35
	v_fma_f32 v34, -v34, v37, v36
	v_div_fmas_f32 v34, v34, v35, v37
	v_div_fixup_f32 v18, v34, v20, v18
	v_mul_f32_e32 v0, v4, v18
	v_mul_f32_e32 v0, v17, v0
	v_mul_f32_e32 v0, v38, v0
	v_cvt_pk_bf16_f32 v4, v0, s0
	v_lshl_add_u64 v[0:1], s[12:13], 0, v[2:3]
	global_store_short v[0:1], v4, off
	v_add_f32_e32 v0, v5, v21
	s_nop 1
	v_add_f32_dpp v0, v0, v0 row_ror:8 row_mask:0xf bank_mask:0xf bound_ctrl:1
	s_nop 1
	v_add_f32_dpp v0, v0, v0 row_ror:4 row_mask:0xf bank_mask:0xf bound_ctrl:1
	s_nop 1
	v_add_f32_dpp v0, v0, v0 row_ror:2 row_mask:0xf bank_mask:0xf bound_ctrl:1
	s_nop 1
	v_add_f32_dpp v0, v0, v0 row_ror:1 row_mask:0xf bank_mask:0xf bound_ctrl:1
	v_mov_b32_e32 v1, v0
	s_nop 1
	v_permlane16_swap_b32_e32 v0, v1
	v_add_f32_e32 v0, v0, v1
	v_fmamk_f32 v4, v0, 0xbc800000, v21
	v_fmamk_f32 v5, v0, 0xbc800000, v5
	v_mul_f32_e32 v0, v4, v4
	v_fmac_f32_e32 v0, v5, v5
	s_nop 1
	v_add_f32_dpp v0, v0, v0 row_ror:8 row_mask:0xf bank_mask:0xf bound_ctrl:1
	s_nop 1
	v_add_f32_dpp v0, v0, v0 row_ror:4 row_mask:0xf bank_mask:0xf bound_ctrl:1
	s_nop 1
	v_add_f32_dpp v0, v0, v0 row_ror:2 row_mask:0xf bank_mask:0xf bound_ctrl:1
	s_nop 1
	v_add_f32_dpp v0, v0, v0 row_ror:1 row_mask:0xf bank_mask:0xf bound_ctrl:1
	v_mov_b32_e32 v1, v0
	s_nop 1
	v_permlane16_swap_b32_e32 v0, v1
	v_add_f32_e32 v0, v0, v1
	v_fmamk_f32 v0, v0, 0x3c800000, v200
	v_cmp_gt_f32_e32 vcc, s43, v0
	v_mul_f32_e32 v1, 0x4f800000, v0
	s_nop 0
	v_cndmask_b32_e32 v0, v0, v1, vcc
	v_sqrt_f32_e32 v1, v0
	s_nop 0
	v_add_u32_e32 v2, -1, v1
	v_fma_f32 v3, -v2, v1, v0
	v_cmp_ge_f32_e64 s[6:7], 0, v3
	v_add_u32_e32 v3, 1, v1
	s_nop 0
	v_cndmask_b32_e64 v2, v1, v2, s[6:7]
	v_fma_f32 v1, -v3, v1, v0
	v_cmp_lt_f32_e64 s[6:7], 0, v1
	s_nop 1
	v_cndmask_b32_e64 v1, v2, v3, s[6:7]
	v_mul_f32_e32 v2, 0x37800000, v1
	v_cndmask_b32_e32 v1, v1, v2, vcc
	v_cmp_class_f32_e32 vcc, v0, v175
	s_nop 1
	v_cndmask_b32_e32 v0, v1, v0, vcc
	v_div_scale_f32 v1, s[6:7], v0, v0, 1.0
	v_rcp_f32_e32 v2, v1
	s_nop 0
	v_fma_f32 v3, -v1, v2, 1.0
	v_fmac_f32_e32 v2, v3, v2
	v_div_scale_f32 v3, vcc, 1.0, v0, 1.0
	v_mul_f32_e32 v16, v3, v2
	v_fma_f32 v17, -v1, v16, v3
	v_fmac_f32_e32 v16, v17, v2
	v_fma_f32 v1, -v1, v16, v3
	v_div_fmas_f32 v1, v1, v2, v16
	v_div_fixup_f32 v16, v1, v0, 1.0
	v_or_b32_e32 v0, 9, v152
	v_mov_b32_e32 v1, v153
	v_lshl_add_u64 v[0:1], v[32:33], 0, v[0:1]
	v_lshlrev_b64 v[0:1], 11, v[0:1]
	v_or_b32_e32 v17, v0, v40
	v_or_b32_e32 v0, 0x600, v17
	v_lshl_add_u64 v[2:3], s[10:11], 0, v[0:1]
	s_nop 0
	v_mov_b32_e32 v3, v1
	v_lshl_add_u64 v[0:1], s[12:13], 0, v[0:1]
	v_lshlrev_b32_e32 v20, 16, v130
	v_or_b32_e32 v2, 0x640, v17
	v_lshl_add_u64 v[18:19], s[10:11], 0, v[2:3]
	s_nop 0
	v_mul_f32_e32 v18, 0xbfb8aa3b, v20
	v_exp_f32_e32 v18, v18
	v_lshlrev_b32_e32 v17, 16, v131
	v_add_f32_e32 v18, 1.0, v18
	v_div_scale_f32 v19, s[6:7], v18, v18, v20
	v_rcp_f32_e32 v21, v19
	s_nop 0
	v_fma_f32 v34, -v19, v21, 1.0
	v_fmac_f32_e32 v21, v34, v21
	v_div_scale_f32 v34, vcc, v20, v18, v20
	v_mul_f32_e32 v35, v34, v21
	v_fma_f32 v36, -v19, v35, v34
	v_fmac_f32_e32 v35, v36, v21
	v_fma_f32 v19, -v19, v35, v34
	v_div_fmas_f32 v19, v19, v21, v35
	v_div_fixup_f32 v18, v19, v18, v20
	v_mul_f32_e32 v19, 0xbfb8aa3b, v17
	v_exp_f32_e32 v19, v19
	v_mul_f32_e32 v5, v5, v18
	v_mul_f32_e32 v5, v16, v5
	v_mul_f32_e32 v5, v39, v5
	v_add_f32_e32 v19, 1.0, v19
	v_div_scale_f32 v20, s[6:7], v19, v19, v17
	v_rcp_f32_e32 v21, v20
	v_cvt_pk_bf16_f32 v5, v5, s0
	global_store_short v[0:1], v5, off
	v_fma_f32 v34, -v20, v21, 1.0
	v_fmac_f32_e32 v21, v34, v21
	v_div_scale_f32 v34, vcc, v17, v19, v17
	v_mul_f32_e32 v35, v34, v21
	v_fma_f32 v36, -v20, v35, v34
	v_fmac_f32_e32 v35, v36, v21
	v_fma_f32 v20, -v20, v35, v34
	v_div_fmas_f32 v20, v20, v21, v35
	v_div_fixup_f32 v17, v20, v19, v17
	v_mul_f32_e32 v0, v4, v17
	v_mul_f32_e32 v0, v16, v0
	v_mul_f32_e32 v0, v38, v0
	v_cvt_pk_bf16_f32 v4, v0, s0
	v_lshl_add_u64 v[0:1], s[12:13], 0, v[2:3]
	global_store_short v[0:1], v4, off
; __device__ __forceinline__ unsigned pk2(float lo, float hi) { return pg8::pk_bf16_rne(lo, hi); }
; __device__ __forceinline__ float bf2f(unsigned short u) { return __uint_as_float(((unsigned)u) << 16); }
; __device__ __forceinline__ float half_sum(float v) { v = row16_allsum(v); v = rows_pair_sum(v); return v; }
; __device__ __forceinline__ int crow(int r, int hi) { return (r & 3) + 8 * (r >> 2) + 4 * hi; }
; __device__ __forceinline__ void ret_out(const Params& P, int l, unsigned char* lds, int u, int tid) {
;     ...
;     for (int r = 0; r < 16; ++r) {
;         const float mean = half_sum(o0[r] + o1[r]) * (1.0f / 64.0f);
;         const float d0 = o0[r] - mean, d1 = o1[r] - mean;
;         const float var = half_sum(d0 * d0 + d1 * d1) * (1.0f / 64.0f);
;         const float rstd = 1.0f / sqrtf(var + 1e-5f);
;         const size_t t = tc + c0f + crow(r, hi);
;         const float ga = bf2f(ZR[t * 1024 + 768 + h * 64 + r32]), gb = bf2f(ZR[t * 1024 + 768 + h * 64 + 32 + r32]);
;         const float sa = ga / (1.0f + __expf(-ga)), sb = gb / (1.0f + __expf(-gb));
;         MIX[t * 1024 + 768 + h * 64 + r32] = (bf16_t)(pk2(sa * d0 * rstd * g0, 0.f) & 0xffffu);
;         MIX[t * 1024 + 768 + h * 64 + 32 + r32] = (bf16_t)(pk2(sb * d1 * rstd * g1, 0.f) & 0xffffu);
;     }
	v_add_f32_e32 v0, v6, v22
	s_nop 1
	v_add_f32_dpp v0, v0, v0 row_ror:8 row_mask:0xf bank_mask:0xf bound_ctrl:1
	s_nop 1
	v_add_f32_dpp v0, v0, v0 row_ror:4 row_mask:0xf bank_mask:0xf bound_ctrl:1
	s_nop 1
	v_add_f32_dpp v0, v0, v0 row_ror:2 row_mask:0xf bank_mask:0xf bound_ctrl:1
	s_nop 1
	v_add_f32_dpp v0, v0, v0 row_ror:1 row_mask:0xf bank_mask:0xf bound_ctrl:1
	v_mov_b32_e32 v1, v0
	s_nop 1
	v_permlane16_swap_b32_e32 v0, v1
	v_add_f32_e32 v0, v0, v1
	v_fmamk_f32 v4, v0, 0xbc800000, v22
	v_fmamk_f32 v5, v0, 0xbc800000, v6
	v_mul_f32_e32 v0, v4, v4
	v_fmac_f32_e32 v0, v5, v5
	s_nop 1
	v_add_f32_dpp v0, v0, v0 row_ror:8 row_mask:0xf bank_mask:0xf bound_ctrl:1
	s_nop 1
	v_add_f32_dpp v0, v0, v0 row_ror:4 row_mask:0xf bank_mask:0xf bound_ctrl:1
	s_nop 1
	v_add_f32_dpp v0, v0, v0 row_ror:2 row_mask:0xf bank_mask:0xf bound_ctrl:1
	s_nop 1
	v_add_f32_dpp v0, v0, v0 row_ror:1 row_mask:0xf bank_mask:0xf bound_ctrl:1
	v_mov_b32_e32 v1, v0
	s_nop 1
	v_permlane16_swap_b32_e32 v0, v1
	v_add_f32_e32 v0, v0, v1
	v_fmamk_f32 v0, v0, 0x3c800000, v200
	v_cmp_gt_f32_e32 vcc, s43, v0
	v_mul_f32_e32 v1, 0x4f800000, v0
	s_nop 0
	v_cndmask_b32_e32 v0, v0, v1, vcc
	v_sqrt_f32_e32 v1, v0
	s_nop 0
	v_add_u32_e32 v2, -1, v1
	v_fma_f32 v3, -v2, v1, v0
	v_cmp_ge_f32_e64 s[6:7], 0, v3
	v_add_u32_e32 v3, 1, v1
	s_nop 0
	v_cndmask_b32_e64 v2, v1, v2, s[6:7]
	v_fma_f32 v1, -v3, v1, v0
	v_cmp_lt_f32_e64 s[6:7], 0, v1
	s_nop 1
	v_cndmask_b32_e64 v1, v2, v3, s[6:7]
	v_mul_f32_e32 v2, 0x37800000, v1
	v_cndmask_b32_e32 v1, v1, v2, vcc
	v_cmp_class_f32_e32 vcc, v0, v175
	s_nop 1
	v_cndmask_b32_e32 v0, v1, v0, vcc
	v_div_scale_f32 v1, s[6:7], v0, v0, 1.0
	v_rcp_f32_e32 v2, v1
	s_nop 0
	v_fma_f32 v3, -v1, v2, 1.0
	v_fmac_f32_e32 v2, v3, v2
	v_div_scale_f32 v3, vcc, 1.0, v0, 1.0
	v_mul_f32_e32 v6, v3, v2
	v_fma_f32 v16, -v1, v6, v3
	v_fmac_f32_e32 v6, v16, v2
	v_fma_f32 v1, -v1, v6, v3
	v_div_fmas_f32 v1, v1, v2, v6
	v_div_fixup_f32 v6, v1, v0, 1.0
	v_or_b32_e32 v0, 10, v152
	v_mov_b32_e32 v1, v153
	v_lshl_add_u64 v[0:1], v[32:33], 0, v[0:1]
	v_lshlrev_b64 v[0:1], 11, v[0:1]
	v_or_b32_e32 v16, v0, v40
	v_or_b32_e32 v0, 0x600, v16
	v_lshl_add_u64 v[2:3], s[10:11], 0, v[0:1]
	s_nop 0
	v_mov_b32_e32 v3, v1
	v_lshl_add_u64 v[0:1], s[12:13], 0, v[0:1]
	v_lshlrev_b32_e32 v18, 16, v132
	v_or_b32_e32 v2, 0x640, v16
	v_lshl_add_u64 v[16:17], s[10:11], 0, v[2:3]
	s_nop 0
	v_mul_f32_e32 v17, 0xbfb8aa3b, v18
	v_exp_f32_e32 v17, v17
	v_lshlrev_b32_e32 v16, 16, v133
	v_add_f32_e32 v17, 1.0, v17
	v_div_scale_f32 v19, s[6:7], v17, v17, v18
	v_rcp_f32_e32 v20, v19
	s_nop 0
	v_fma_f32 v21, -v19, v20, 1.0
	v_fmac_f32_e32 v20, v21, v20
	v_div_scale_f32 v21, vcc, v18, v17, v18
	v_mul_f32_e32 v22, v21, v20
	v_fma_f32 v34, -v19, v22, v21
	v_fmac_f32_e32 v22, v34, v20
	v_fma_f32 v19, -v19, v22, v21
	v_div_fmas_f32 v19, v19, v20, v22
	v_div_fixup_f32 v17, v19, v17, v18
	v_mul_f32_e32 v18, 0xbfb8aa3b, v16
	v_exp_f32_e32 v18, v18
	v_mul_f32_e32 v5, v5, v17
	v_mul_f32_e32 v5, v6, v5
	v_mul_f32_e32 v5, v39, v5
	v_add_f32_e32 v18, 1.0, v18
	v_div_scale_f32 v19, s[6:7], v18, v18, v16
	v_rcp_f32_e32 v20, v19
	v_cvt_pk_bf16_f32 v5, v5, s0
	global_store_short v[0:1], v5, off
	v_fma_f32 v21, -v19, v20, 1.0
	v_fmac_f32_e32 v20, v21, v20
	v_div_scale_f32 v21, vcc, v16, v18, v16
	v_mul_f32_e32 v22, v21, v20
	v_fma_f32 v34, -v19, v22, v21
	v_fmac_f32_e32 v22, v34, v20
	v_fma_f32 v19, -v19, v22, v21
	v_div_fmas_f32 v19, v19, v20, v22
	v_div_fixup_f32 v16, v19, v18, v16
	v_mul_f32_e32 v0, v4, v16
	v_mul_f32_e32 v0, v6, v0
	v_mul_f32_e32 v0, v38, v0
	v_cvt_pk_bf16_f32 v4, v0, s0
	v_lshl_add_u64 v[0:1], s[12:13], 0, v[2:3]
	global_store_short v[0:1], v4, off
	v_add_f32_e32 v0, v7, v23
	s_nop 1
	v_add_f32_dpp v0, v0, v0 row_ror:8 row_mask:0xf bank_mask:0xf bound_ctrl:1
	s_nop 1
	v_add_f32_dpp v0, v0, v0 row_ror:4 row_mask:0xf bank_mask:0xf bound_ctrl:1
	s_nop 1
	v_add_f32_dpp v0, v0, v0 row_ror:2 row_mask:0xf bank_mask:0xf bound_ctrl:1
	s_nop 1
	v_add_f32_dpp v0, v0, v0 row_ror:1 row_mask:0xf bank_mask:0xf bound_ctrl:1
	v_mov_b32_e32 v1, v0
	s_nop 1
	v_permlane16_swap_b32_e32 v0, v1
	v_add_f32_e32 v0, v0, v1
	v_fmamk_f32 v4, v0, 0xbc800000, v23
	v_fmamk_f32 v5, v0, 0xbc800000, v7
	v_mul_f32_e32 v0, v4, v4
	v_fmac_f32_e32 v0, v5, v5
	s_nop 1
	v_add_f32_dpp v0, v0, v0 row_ror:8 row_mask:0xf bank_mask:0xf bound_ctrl:1
	s_nop 1
	v_add_f32_dpp v0, v0, v0 row_ror:4 row_mask:0xf bank_mask:0xf bound_ctrl:1
	s_nop 1
	v_add_f32_dpp v0, v0, v0 row_ror:2 row_mask:0xf bank_mask:0xf bound_ctrl:1
	s_nop 1
	v_add_f32_dpp v0, v0, v0 row_ror:1 row_mask:0xf bank_mask:0xf bound_ctrl:1
	v_mov_b32_e32 v1, v0
	s_nop 1
	v_permlane16_swap_b32_e32 v0, v1
	v_add_f32_e32 v0, v0, v1
	v_fmamk_f32 v0, v0, 0x3c800000, v200
	v_cmp_gt_f32_e32 vcc, s43, v0
	v_mul_f32_e32 v1, 0x4f800000, v0
	s_nop 0
	v_cndmask_b32_e32 v0, v0, v1, vcc
	v_sqrt_f32_e32 v1, v0
	s_nop 0
	v_add_u32_e32 v2, -1, v1
	v_fma_f32 v3, -v2, v1, v0
	v_cmp_ge_f32_e64 s[6:7], 0, v3
	v_add_u32_e32 v3, 1, v1
	s_nop 0
	v_cndmask_b32_e64 v2, v1, v2, s[6:7]
	v_fma_f32 v1, -v3, v1, v0
	v_cmp_lt_f32_e64 s[6:7], 0, v1
	s_nop 1
	v_cndmask_b32_e64 v1, v2, v3, s[6:7]
	v_mul_f32_e32 v2, 0x37800000, v1
	v_cndmask_b32_e32 v1, v1, v2, vcc
	v_cmp_class_f32_e32 vcc, v0, v175
	s_nop 1
	v_cndmask_b32_e32 v0, v1, v0, vcc
	v_div_scale_f32 v1, s[6:7], v0, v0, 1.0
	v_rcp_f32_e32 v2, v1
	s_nop 0
	v_fma_f32 v3, -v1, v2, 1.0
	v_fmac_f32_e32 v2, v3, v2
	v_div_scale_f32 v3, vcc, 1.0, v0, 1.0
	v_mul_f32_e32 v6, v3, v2
	v_fma_f32 v7, -v1, v6, v3
	v_fmac_f32_e32 v6, v7, v2
	v_fma_f32 v1, -v1, v6, v3
	v_div_fmas_f32 v1, v1, v2, v6
	v_div_fixup_f32 v6, v1, v0, 1.0
	v_or_b32_e32 v0, 11, v152
	v_mov_b32_e32 v1, v153
; __device__ __forceinline__ unsigned pk2(float lo, float hi) { return pg8::pk_bf16_rne(lo, hi); }
; __device__ __forceinline__ float bf2f(unsigned short u) { return __uint_as_float(((unsigned)u) << 16); }
; __device__ __forceinline__ float half_sum(float v) { v = row16_allsum(v); v = rows_pair_sum(v); return v; }
; __device__ __forceinline__ int crow(int r, int hi) { return (r & 3) + 8 * (r >> 2) + 4 * hi; }
; __device__ __forceinline__ void ret_out(const Params& P, int l, unsigned char* lds, int u, int tid) {
;     ...
;     for (int r = 0; r < 16; ++r) {
;         const float mean = half_sum(o0[r] + o1[r]) * (1.0f / 64.0f);
;         const float d0 = o0[r] - mean, d1 = o1[r] - mean;
;         const float var = half_sum(d0 * d0 + d1 * d1) * (1.0f / 64.0f);
;         const float rstd = 1.0f / sqrtf(var + 1e-5f);
;         const size_t t = tc + c0f + crow(r, hi);
;         const float ga = bf2f(ZR[t * 1024 + 768 + h * 64 + r32]), gb = bf2f(ZR[t * 1024 + 768 + h * 64 + 32 + r32]);
;         const float sa = ga / (1.0f + __expf(-ga)), sb = gb / (1.0f + __expf(-gb));
;         MIX[t * 1024 + 768 + h * 64 + r32] = (bf16_t)(pk2(sa * d0 * rstd * g0, 0.f) & 0xffffu);
;         MIX[t * 1024 + 768 + h * 64 + 32 + r32] = (bf16_t)(pk2(sb * d1 * rstd * g1, 0.f) & 0xffffu);
;     }
	v_lshl_add_u64 v[0:1], v[32:33], 0, v[0:1]
	v_lshlrev_b64 v[0:1], 11, v[0:1]
	v_or_b32_e32 v7, v0, v40
	v_or_b32_e32 v0, 0x600, v7
	v_lshl_add_u64 v[2:3], s[10:11], 0, v[0:1]
	s_nop 0
	v_mov_b32_e32 v3, v1
	v_lshl_add_u64 v[0:1], s[12:13], 0, v[0:1]
	v_lshlrev_b32_e32 v18, 16, v134
	v_or_b32_e32 v2, 0x640, v7
	v_lshl_add_u64 v[16:17], s[10:11], 0, v[2:3]
	s_nop 0
	v_mul_f32_e32 v16, 0xbfb8aa3b, v18
	v_exp_f32_e32 v16, v16
	v_lshlrev_b32_e32 v7, 16, v135
	v_add_f32_e32 v16, 1.0, v16
	v_div_scale_f32 v17, s[6:7], v16, v16, v18
	v_rcp_f32_e32 v19, v17
	s_nop 0
	v_fma_f32 v20, -v17, v19, 1.0
	v_fmac_f32_e32 v19, v20, v19
	v_div_scale_f32 v20, vcc, v18, v16, v18
	v_mul_f32_e32 v21, v20, v19
	v_fma_f32 v22, -v17, v21, v20
	v_fmac_f32_e32 v21, v22, v19
	v_fma_f32 v17, -v17, v21, v20
	v_div_fmas_f32 v17, v17, v19, v21
	v_div_fixup_f32 v16, v17, v16, v18
	v_mul_f32_e32 v17, 0xbfb8aa3b, v7
	v_exp_f32_e32 v17, v17
	v_mul_f32_e32 v5, v5, v16
	v_mul_f32_e32 v5, v6, v5
	v_mul_f32_e32 v5, v39, v5
	v_add_f32_e32 v17, 1.0, v17
	v_div_scale_f32 v18, s[6:7], v17, v17, v7
	v_rcp_f32_e32 v19, v18
	v_cvt_pk_bf16_f32 v5, v5, s0
	global_store_short v[0:1], v5, off
	v_fma_f32 v20, -v18, v19, 1.0
	v_fmac_f32_e32 v19, v20, v19
	v_div_scale_f32 v20, vcc, v7, v17, v7
	v_mul_f32_e32 v21, v20, v19
	v_fma_f32 v22, -v18, v21, v20
	v_fmac_f32_e32 v21, v22, v19
	v_fma_f32 v18, -v18, v21, v20
	v_div_fmas_f32 v18, v18, v19, v21
	v_div_fixup_f32 v7, v18, v17, v7
	v_mul_f32_e32 v0, v4, v7
	v_mul_f32_e32 v0, v6, v0
	v_mul_f32_e32 v0, v38, v0
	v_cvt_pk_bf16_f32 v4, v0, s0
	v_lshl_add_u64 v[0:1], s[12:13], 0, v[2:3]
	global_store_short v[0:1], v4, off
	v_add_f32_e32 v0, v8, v24
	s_nop 1
	v_add_f32_dpp v0, v0, v0 row_ror:8 row_mask:0xf bank_mask:0xf bound_ctrl:1
	s_nop 1
	v_add_f32_dpp v0, v0, v0 row_ror:4 row_mask:0xf bank_mask:0xf bound_ctrl:1
	s_nop 1
	v_add_f32_dpp v0, v0, v0 row_ror:2 row_mask:0xf bank_mask:0xf bound_ctrl:1
	s_nop 1
	v_add_f32_dpp v0, v0, v0 row_ror:1 row_mask:0xf bank_mask:0xf bound_ctrl:1
	v_mov_b32_e32 v1, v0
	s_nop 1
	v_permlane16_swap_b32_e32 v0, v1
	v_add_f32_e32 v0, v0, v1
	v_fmamk_f32 v4, v0, 0xbc800000, v24
	v_fmamk_f32 v5, v0, 0xbc800000, v8
	v_mul_f32_e32 v0, v4, v4
	v_fmac_f32_e32 v0, v5, v5
	s_nop 1
	v_add_f32_dpp v0, v0, v0 row_ror:8 row_mask:0xf bank_mask:0xf bound_ctrl:1
	s_nop 1
	v_add_f32_dpp v0, v0, v0 row_ror:4 row_mask:0xf bank_mask:0xf bound_ctrl:1
	s_nop 1
	v_add_f32_dpp v0, v0, v0 row_ror:2 row_mask:0xf bank_mask:0xf bound_ctrl:1
	s_nop 1
	v_add_f32_dpp v0, v0, v0 row_ror:1 row_mask:0xf bank_mask:0xf bound_ctrl:1
	v_mov_b32_e32 v1, v0
	s_nop 1
	v_permlane16_swap_b32_e32 v0, v1
	v_add_f32_e32 v0, v0, v1
	v_fmamk_f32 v0, v0, 0x3c800000, v200
	v_cmp_gt_f32_e32 vcc, s43, v0
	v_mul_f32_e32 v1, 0x4f800000, v0
	s_nop 0
	v_cndmask_b32_e32 v0, v0, v1, vcc
	v_sqrt_f32_e32 v1, v0
	s_nop 0
	v_add_u32_e32 v2, -1, v1
	v_fma_f32 v3, -v2, v1, v0
	v_cmp_ge_f32_e64 s[6:7], 0, v3
	v_add_u32_e32 v3, 1, v1
	s_nop 0
	v_cndmask_b32_e64 v2, v1, v2, s[6:7]
	v_fma_f32 v1, -v3, v1, v0
	v_cmp_lt_f32_e64 s[6:7], 0, v1
	s_nop 1
	v_cndmask_b32_e64 v1, v2, v3, s[6:7]
	v_mul_f32_e32 v2, 0x37800000, v1
	v_cndmask_b32_e32 v1, v1, v2, vcc
	v_cmp_class_f32_e32 vcc, v0, v175
	s_nop 1
	v_cndmask_b32_e32 v0, v1, v0, vcc
	v_div_scale_f32 v1, s[6:7], v0, v0, 1.0
	v_rcp_f32_e32 v2, v1
	s_nop 0
	v_fma_f32 v3, -v1, v2, 1.0
	v_fmac_f32_e32 v2, v3, v2
	v_div_scale_f32 v3, vcc, 1.0, v0, 1.0
	v_mul_f32_e32 v6, v3, v2
	v_fma_f32 v7, -v1, v6, v3
	v_fmac_f32_e32 v6, v7, v2
	v_fma_f32 v1, -v1, v6, v3
	v_div_fmas_f32 v1, v1, v2, v6
	v_div_fixup_f32 v6, v1, v0, 1.0
	v_or_b32_e32 v0, 16, v152
	v_mov_b32_e32 v1, v153
	v_lshl_add_u64 v[0:1], v[32:33], 0, v[0:1]
	v_lshlrev_b64 v[0:1], 11, v[0:1]
	v_or_b32_e32 v7, v0, v40
	v_or_b32_e32 v0, 0x600, v7
	v_lshl_add_u64 v[2:3], s[10:11], 0, v[0:1]
	s_nop 0
	v_mov_b32_e32 v3, v1
	v_lshl_add_u64 v[0:1], s[12:13], 0, v[0:1]
	v_lshlrev_b32_e32 v8, 16, v136
	v_or_b32_e32 v2, 0x640, v7
	v_lshl_add_u64 v[16:17], s[10:11], 0, v[2:3]
	s_nop 0
	v_mul_f32_e32 v16, 0xbfb8aa3b, v8
	v_exp_f32_e32 v16, v16
	v_lshlrev_b32_e32 v7, 16, v137
	v_add_f32_e32 v16, 1.0, v16
	v_div_scale_f32 v17, s[6:7], v16, v16, v8
	v_rcp_f32_e32 v18, v17
	s_nop 0
	v_fma_f32 v19, -v17, v18, 1.0
	v_fmac_f32_e32 v18, v19, v18
	v_div_scale_f32 v19, vcc, v8, v16, v8
	v_mul_f32_e32 v20, v19, v18
	v_fma_f32 v21, -v17, v20, v19
	v_fmac_f32_e32 v20, v21, v18
	v_fma_f32 v17, -v17, v20, v19
	v_div_fmas_f32 v17, v17, v18, v20
	v_div_fixup_f32 v8, v17, v16, v8
	v_mul_f32_e32 v16, 0xbfb8aa3b, v7
	v_exp_f32_e32 v16, v16
	v_mul_f32_e32 v5, v5, v8
	v_mul_f32_e32 v5, v6, v5
	v_mul_f32_e32 v5, v39, v5
	v_add_f32_e32 v16, 1.0, v16
	v_div_scale_f32 v17, s[6:7], v16, v16, v7
	v_rcp_f32_e32 v18, v17
	v_cvt_pk_bf16_f32 v5, v5, s0
	global_store_short v[0:1], v5, off
	v_fma_f32 v19, -v17, v18, 1.0
	v_fmac_f32_e32 v18, v19, v18
	v_div_scale_f32 v19, vcc, v7, v16, v7
	v_mul_f32_e32 v20, v19, v18
	v_fma_f32 v21, -v17, v20, v19
	v_fmac_f32_e32 v20, v21, v18
	v_fma_f32 v17, -v17, v20, v19
	v_div_fmas_f32 v17, v17, v18, v20
	v_div_fixup_f32 v7, v17, v16, v7
	v_mul_f32_e32 v0, v4, v7
	v_mul_f32_e32 v0, v6, v0
	v_mul_f32_e32 v0, v38, v0
	v_cvt_pk_bf16_f32 v4, v0, s0
	v_lshl_add_u64 v[0:1], s[12:13], 0, v[2:3]
	global_store_short v[0:1], v4, off
	v_add_f32_e32 v0, v9, v25
	s_nop 1
	v_add_f32_dpp v0, v0, v0 row_ror:8 row_mask:0xf bank_mask:0xf bound_ctrl:1
	s_nop 1
	v_add_f32_dpp v0, v0, v0 row_ror:4 row_mask:0xf bank_mask:0xf bound_ctrl:1
	s_nop 1
	v_add_f32_dpp v0, v0, v0 row_ror:2 row_mask:0xf bank_mask:0xf bound_ctrl:1
	s_nop 1
	v_add_f32_dpp v0, v0, v0 row_ror:1 row_mask:0xf bank_mask:0xf bound_ctrl:1
; __device__ __forceinline__ unsigned pk2(float lo, float hi) { return pg8::pk_bf16_rne(lo, hi); }
; __device__ __forceinline__ float bf2f(unsigned short u) { return __uint_as_float(((unsigned)u) << 16); }
; __device__ __forceinline__ float half_sum(float v) { v = row16_allsum(v); v = rows_pair_sum(v); return v; }
; __device__ __forceinline__ int crow(int r, int hi) { return (r & 3) + 8 * (r >> 2) + 4 * hi; }
; __device__ __forceinline__ void ret_out(const Params& P, int l, unsigned char* lds, int u, int tid) {
;     ...
;     for (int r = 0; r < 16; ++r) {
;         const float mean = half_sum(o0[r] + o1[r]) * (1.0f / 64.0f);
;         const float d0 = o0[r] - mean, d1 = o1[r] - mean;
;         const float var = half_sum(d0 * d0 + d1 * d1) * (1.0f / 64.0f);
;         const float rstd = 1.0f / sqrtf(var + 1e-5f);
;         const size_t t = tc + c0f + crow(r, hi);
;         const float ga = bf2f(ZR[t * 1024 + 768 + h * 64 + r32]), gb = bf2f(ZR[t * 1024 + 768 + h * 64 + 32 + r32]);
;         const float sa = ga / (1.0f + __expf(-ga)), sb = gb / (1.0f + __expf(-gb));
;         MIX[t * 1024 + 768 + h * 64 + r32] = (bf16_t)(pk2(sa * d0 * rstd * g0, 0.f) & 0xffffu);
;         MIX[t * 1024 + 768 + h * 64 + 32 + r32] = (bf16_t)(pk2(sb * d1 * rstd * g1, 0.f) & 0xffffu);
;     }
	v_mov_b32_e32 v1, v0
	s_nop 1
	v_permlane16_swap_b32_e32 v0, v1
	v_add_f32_e32 v0, v0, v1
	v_fmamk_f32 v4, v0, 0xbc800000, v25
	v_fmamk_f32 v5, v0, 0xbc800000, v9
	v_mul_f32_e32 v0, v4, v4
	v_fmac_f32_e32 v0, v5, v5
	s_nop 1
	v_add_f32_dpp v0, v0, v0 row_ror:8 row_mask:0xf bank_mask:0xf bound_ctrl:1
	s_nop 1
	v_add_f32_dpp v0, v0, v0 row_ror:4 row_mask:0xf bank_mask:0xf bound_ctrl:1
	s_nop 1
	v_add_f32_dpp v0, v0, v0 row_ror:2 row_mask:0xf bank_mask:0xf bound_ctrl:1
	s_nop 1
	v_add_f32_dpp v0, v0, v0 row_ror:1 row_mask:0xf bank_mask:0xf bound_ctrl:1
	v_mov_b32_e32 v1, v0
	s_nop 1
	v_permlane16_swap_b32_e32 v0, v1
	v_add_f32_e32 v0, v0, v1
	v_fmamk_f32 v0, v0, 0x3c800000, v200
	v_cmp_gt_f32_e32 vcc, s43, v0
	v_mul_f32_e32 v1, 0x4f800000, v0
	s_nop 0
	v_cndmask_b32_e32 v0, v0, v1, vcc
	v_sqrt_f32_e32 v1, v0
	s_nop 0
	v_add_u32_e32 v2, -1, v1
	v_fma_f32 v3, -v2, v1, v0
	v_cmp_ge_f32_e64 s[6:7], 0, v3
	v_add_u32_e32 v3, 1, v1
	s_nop 0
	v_cndmask_b32_e64 v2, v1, v2, s[6:7]
	v_fma_f32 v1, -v3, v1, v0
	v_cmp_lt_f32_e64 s[6:7], 0, v1
	s_nop 1
	v_cndmask_b32_e64 v1, v2, v3, s[6:7]
	v_mul_f32_e32 v2, 0x37800000, v1
	v_cndmask_b32_e32 v1, v1, v2, vcc
	v_cmp_class_f32_e32 vcc, v0, v175
	s_nop 1
	v_cndmask_b32_e32 v0, v1, v0, vcc
	v_div_scale_f32 v1, s[6:7], v0, v0, 1.0
	v_rcp_f32_e32 v2, v1
	s_nop 0
	v_fma_f32 v3, -v1, v2, 1.0
	v_fmac_f32_e32 v2, v3, v2
	v_div_scale_f32 v3, vcc, 1.0, v0, 1.0
	v_mul_f32_e32 v6, v3, v2
	v_fma_f32 v7, -v1, v6, v3
	v_fmac_f32_e32 v6, v7, v2
	v_fma_f32 v1, -v1, v6, v3
	v_div_fmas_f32 v1, v1, v2, v6
	v_div_fixup_f32 v6, v1, v0, 1.0
	v_or_b32_e32 v0, 17, v152
	v_mov_b32_e32 v1, v153
	v_lshl_add_u64 v[0:1], v[32:33], 0, v[0:1]
	v_lshlrev_b64 v[0:1], 11, v[0:1]
	v_or_b32_e32 v7, v0, v40
	v_or_b32_e32 v0, 0x600, v7
	v_lshl_add_u64 v[2:3], s[10:11], 0, v[0:1]
	s_nop 0
	v_mov_b32_e32 v3, v1
	v_lshl_add_u64 v[0:1], s[12:13], 0, v[0:1]
	v_lshlrev_b32_e32 v16, 16, v138
	v_or_b32_e32 v2, 0x640, v7
	v_lshl_add_u64 v[8:9], s[10:11], 0, v[2:3]
	s_nop 0
	v_mul_f32_e32 v8, 0xbfb8aa3b, v16
	v_exp_f32_e32 v8, v8
	v_lshlrev_b32_e32 v7, 16, v139
	v_add_f32_e32 v8, 1.0, v8
	v_div_scale_f32 v9, s[6:7], v8, v8, v16
	v_rcp_f32_e32 v17, v9
	s_nop 0
	v_fma_f32 v18, -v9, v17, 1.0
	v_fmac_f32_e32 v17, v18, v17
	v_div_scale_f32 v18, vcc, v16, v8, v16
	v_mul_f32_e32 v19, v18, v17
	v_fma_f32 v20, -v9, v19, v18
	v_fmac_f32_e32 v19, v20, v17
	v_fma_f32 v9, -v9, v19, v18
	v_div_fmas_f32 v9, v9, v17, v19
	v_div_fixup_f32 v8, v9, v8, v16
	v_mul_f32_e32 v9, 0xbfb8aa3b, v7
	v_exp_f32_e32 v9, v9
	v_mul_f32_e32 v5, v5, v8
	v_mul_f32_e32 v5, v6, v5
	v_mul_f32_e32 v5, v39, v5
	v_add_f32_e32 v9, 1.0, v9
	v_div_scale_f32 v16, s[6:7], v9, v9, v7
	v_rcp_f32_e32 v17, v16
	v_cvt_pk_bf16_f32 v5, v5, s0
	global_store_short v[0:1], v5, off
	v_fma_f32 v18, -v16, v17, 1.0
	v_fmac_f32_e32 v17, v18, v17
	v_div_scale_f32 v18, vcc, v7, v9, v7
	v_mul_f32_e32 v19, v18, v17
	v_fma_f32 v20, -v16, v19, v18
	v_fmac_f32_e32 v19, v20, v17
	v_fma_f32 v16, -v16, v19, v18
	v_div_fmas_f32 v16, v16, v17, v19
	v_div_fixup_f32 v7, v16, v9, v7
	v_mul_f32_e32 v0, v4, v7
	v_mul_f32_e32 v0, v6, v0
	v_mul_f32_e32 v0, v38, v0
	v_cvt_pk_bf16_f32 v4, v0, s0
	v_lshl_add_u64 v[0:1], s[12:13], 0, v[2:3]
	global_store_short v[0:1], v4, off
	v_add_f32_e32 v0, v10, v26
	s_nop 1
	v_add_f32_dpp v0, v0, v0 row_ror:8 row_mask:0xf bank_mask:0xf bound_ctrl:1
	s_nop 1
	v_add_f32_dpp v0, v0, v0 row_ror:4 row_mask:0xf bank_mask:0xf bound_ctrl:1
	s_nop 1
	v_add_f32_dpp v0, v0, v0 row_ror:2 row_mask:0xf bank_mask:0xf bound_ctrl:1
	s_nop 1
	v_add_f32_dpp v0, v0, v0 row_ror:1 row_mask:0xf bank_mask:0xf bound_ctrl:1
	v_mov_b32_e32 v1, v0
	s_nop 1
	v_permlane16_swap_b32_e32 v0, v1
	v_add_f32_e32 v0, v0, v1
	v_fmamk_f32 v4, v0, 0xbc800000, v26
	v_fmamk_f32 v5, v0, 0xbc800000, v10
	v_mul_f32_e32 v0, v4, v4
	v_fmac_f32_e32 v0, v5, v5
	s_nop 1
	v_add_f32_dpp v0, v0, v0 row_ror:8 row_mask:0xf bank_mask:0xf bound_ctrl:1
	s_nop 1
	v_add_f32_dpp v0, v0, v0 row_ror:4 row_mask:0xf bank_mask:0xf bound_ctrl:1
	s_nop 1
	v_add_f32_dpp v0, v0, v0 row_ror:2 row_mask:0xf bank_mask:0xf bound_ctrl:1
	s_nop 1
	v_add_f32_dpp v0, v0, v0 row_ror:1 row_mask:0xf bank_mask:0xf bound_ctrl:1
	v_mov_b32_e32 v1, v0
	s_nop 1
	v_permlane16_swap_b32_e32 v0, v1
	v_add_f32_e32 v0, v0, v1
	v_fmamk_f32 v0, v0, 0x3c800000, v200
	v_cmp_gt_f32_e32 vcc, s43, v0
	v_mul_f32_e32 v1, 0x4f800000, v0
	s_nop 0
	v_cndmask_b32_e32 v0, v0, v1, vcc
	v_sqrt_f32_e32 v1, v0
	s_nop 0
	v_add_u32_e32 v2, -1, v1
	v_fma_f32 v3, -v2, v1, v0
	v_cmp_ge_f32_e64 s[6:7], 0, v3
	v_add_u32_e32 v3, 1, v1
	s_nop 0
	v_cndmask_b32_e64 v2, v1, v2, s[6:7]
	v_fma_f32 v1, -v3, v1, v0
	v_cmp_lt_f32_e64 s[6:7], 0, v1
	s_nop 1
	v_cndmask_b32_e64 v1, v2, v3, s[6:7]
	v_mul_f32_e32 v2, 0x37800000, v1
	v_cndmask_b32_e32 v1, v1, v2, vcc
	v_cmp_class_f32_e32 vcc, v0, v175
	s_nop 1
	v_cndmask_b32_e32 v0, v1, v0, vcc
	v_div_scale_f32 v1, s[6:7], v0, v0, 1.0
	v_rcp_f32_e32 v2, v1
	s_nop 0
	v_fma_f32 v3, -v1, v2, 1.0
	v_fmac_f32_e32 v2, v3, v2
	v_div_scale_f32 v3, vcc, 1.0, v0, 1.0
	v_mul_f32_e32 v6, v3, v2
	v_fma_f32 v7, -v1, v6, v3
	v_fmac_f32_e32 v6, v7, v2
	v_fma_f32 v1, -v1, v6, v3
	v_div_fmas_f32 v1, v1, v2, v6
	v_div_fixup_f32 v6, v1, v0, 1.0
	v_or_b32_e32 v0, 18, v152
	v_mov_b32_e32 v1, v153
	v_lshl_add_u64 v[0:1], v[32:33], 0, v[0:1]
	v_lshlrev_b64 v[0:1], 11, v[0:1]
	v_or_b32_e32 v7, v0, v40
	v_or_b32_e32 v0, 0x600, v7
	v_lshl_add_u64 v[2:3], s[10:11], 0, v[0:1]
	s_nop 0
	v_mov_b32_e32 v3, v1
	v_lshl_add_u64 v[0:1], s[12:13], 0, v[0:1]
	v_lshlrev_b32_e32 v10, 16, v140
	v_or_b32_e32 v2, 0x640, v7
	v_lshl_add_u64 v[8:9], s[10:11], 0, v[2:3]
	s_nop 0
	v_mul_f32_e32 v8, 0xbfb8aa3b, v10
; __device__ __forceinline__ unsigned pk2(float lo, float hi) { return pg8::pk_bf16_rne(lo, hi); }
; __device__ __forceinline__ float bf2f(unsigned short u) { return __uint_as_float(((unsigned)u) << 16); }
; __device__ __forceinline__ float half_sum(float v) { v = row16_allsum(v); v = rows_pair_sum(v); return v; }
; __device__ __forceinline__ int crow(int r, int hi) { return (r & 3) + 8 * (r >> 2) + 4 * hi; }
; __device__ __forceinline__ void ret_out(const Params& P, int l, unsigned char* lds, int u, int tid) {
;     ...
;     for (int r = 0; r < 16; ++r) {
;         const float mean = half_sum(o0[r] + o1[r]) * (1.0f / 64.0f);
;         const float d0 = o0[r] - mean, d1 = o1[r] - mean;
;         const float var = half_sum(d0 * d0 + d1 * d1) * (1.0f / 64.0f);
;         const float rstd = 1.0f / sqrtf(var + 1e-5f);
;         const size_t t = tc + c0f + crow(r, hi);
;         const float ga = bf2f(ZR[t * 1024 + 768 + h * 64 + r32]), gb = bf2f(ZR[t * 1024 + 768 + h * 64 + 32 + r32]);
;         const float sa = ga / (1.0f + __expf(-ga)), sb = gb / (1.0f + __expf(-gb));
;         MIX[t * 1024 + 768 + h * 64 + r32] = (bf16_t)(pk2(sa * d0 * rstd * g0, 0.f) & 0xffffu);
;         MIX[t * 1024 + 768 + h * 64 + 32 + r32] = (bf16_t)(pk2(sb * d1 * rstd * g1, 0.f) & 0xffffu);
;     }
	v_exp_f32_e32 v8, v8
	v_lshlrev_b32_e32 v7, 16, v141
	v_add_f32_e32 v8, 1.0, v8
	v_div_scale_f32 v9, s[6:7], v8, v8, v10
	v_rcp_f32_e32 v16, v9
	s_nop 0
	v_fma_f32 v17, -v9, v16, 1.0
	v_fmac_f32_e32 v16, v17, v16
	v_div_scale_f32 v17, vcc, v10, v8, v10
	v_mul_f32_e32 v18, v17, v16
	v_fma_f32 v19, -v9, v18, v17
	v_fmac_f32_e32 v18, v19, v16
	v_fma_f32 v9, -v9, v18, v17
	v_div_fmas_f32 v9, v9, v16, v18
	v_div_fixup_f32 v8, v9, v8, v10
	v_mul_f32_e32 v9, 0xbfb8aa3b, v7
	v_exp_f32_e32 v9, v9
	v_mul_f32_e32 v5, v5, v8
	v_mul_f32_e32 v5, v6, v5
	v_mul_f32_e32 v5, v39, v5
	v_add_f32_e32 v9, 1.0, v9
	v_div_scale_f32 v10, s[6:7], v9, v9, v7
	v_rcp_f32_e32 v16, v10
	v_cvt_pk_bf16_f32 v5, v5, s0
	global_store_short v[0:1], v5, off
	v_fma_f32 v17, -v10, v16, 1.0
	v_fmac_f32_e32 v16, v17, v16
	v_div_scale_f32 v17, vcc, v7, v9, v7
	v_mul_f32_e32 v18, v17, v16
	v_fma_f32 v19, -v10, v18, v17
	v_fmac_f32_e32 v18, v19, v16
	v_fma_f32 v10, -v10, v18, v17
	v_div_fmas_f32 v10, v10, v16, v18
	v_div_fixup_f32 v7, v10, v9, v7
	v_mul_f32_e32 v0, v4, v7
	v_mul_f32_e32 v0, v6, v0
	v_mul_f32_e32 v0, v38, v0
	v_cvt_pk_bf16_f32 v4, v0, s0
	v_lshl_add_u64 v[0:1], s[12:13], 0, v[2:3]
	global_store_short v[0:1], v4, off
	v_add_f32_e32 v0, v11, v27
	s_nop 1
	v_add_f32_dpp v0, v0, v0 row_ror:8 row_mask:0xf bank_mask:0xf bound_ctrl:1
	s_nop 1
	v_add_f32_dpp v0, v0, v0 row_ror:4 row_mask:0xf bank_mask:0xf bound_ctrl:1
	s_nop 1
	v_add_f32_dpp v0, v0, v0 row_ror:2 row_mask:0xf bank_mask:0xf bound_ctrl:1
	s_nop 1
	v_add_f32_dpp v0, v0, v0 row_ror:1 row_mask:0xf bank_mask:0xf bound_ctrl:1
	v_mov_b32_e32 v1, v0
	s_nop 1
	v_permlane16_swap_b32_e32 v0, v1
	v_add_f32_e32 v0, v0, v1
	v_fmamk_f32 v4, v0, 0xbc800000, v27
	v_fmamk_f32 v5, v0, 0xbc800000, v11
	v_mul_f32_e32 v0, v4, v4
	v_fmac_f32_e32 v0, v5, v5
	s_nop 1
	v_add_f32_dpp v0, v0, v0 row_ror:8 row_mask:0xf bank_mask:0xf bound_ctrl:1
	s_nop 1
	v_add_f32_dpp v0, v0, v0 row_ror:4 row_mask:0xf bank_mask:0xf bound_ctrl:1
	s_nop 1
	v_add_f32_dpp v0, v0, v0 row_ror:2 row_mask:0xf bank_mask:0xf bound_ctrl:1
	s_nop 1
	v_add_f32_dpp v0, v0, v0 row_ror:1 row_mask:0xf bank_mask:0xf bound_ctrl:1
	v_mov_b32_e32 v1, v0
	s_nop 1
	v_permlane16_swap_b32_e32 v0, v1
	v_add_f32_e32 v0, v0, v1
	v_fmamk_f32 v0, v0, 0x3c800000, v200
	v_cmp_gt_f32_e32 vcc, s43, v0
	v_mul_f32_e32 v1, 0x4f800000, v0
	s_nop 0
	v_cndmask_b32_e32 v0, v0, v1, vcc
	v_sqrt_f32_e32 v1, v0
	s_nop 0
	v_add_u32_e32 v2, -1, v1
	v_fma_f32 v3, -v2, v1, v0
	v_cmp_ge_f32_e64 s[6:7], 0, v3
	v_add_u32_e32 v3, 1, v1
	s_nop 0
	v_cndmask_b32_e64 v2, v1, v2, s[6:7]
	v_fma_f32 v1, -v3, v1, v0
	v_cmp_lt_f32_e64 s[6:7], 0, v1
	s_nop 1
	v_cndmask_b32_e64 v1, v2, v3, s[6:7]
	v_mul_f32_e32 v2, 0x37800000, v1
	v_cndmask_b32_e32 v1, v1, v2, vcc
	v_cmp_class_f32_e32 vcc, v0, v175
	s_nop 1
	v_cndmask_b32_e32 v0, v1, v0, vcc
	v_div_scale_f32 v1, s[6:7], v0, v0, 1.0
	v_rcp_f32_e32 v2, v1
	s_nop 0
	v_fma_f32 v3, -v1, v2, 1.0
	v_fmac_f32_e32 v2, v3, v2
	v_div_scale_f32 v3, vcc, 1.0, v0, 1.0
	v_mul_f32_e32 v6, v3, v2
	v_fma_f32 v7, -v1, v6, v3
	v_fmac_f32_e32 v6, v7, v2
	v_fma_f32 v1, -v1, v6, v3
	v_div_fmas_f32 v1, v1, v2, v6
	v_div_fixup_f32 v6, v1, v0, 1.0
	v_or_b32_e32 v0, 19, v152
	v_mov_b32_e32 v1, v153
	v_lshl_add_u64 v[0:1], v[32:33], 0, v[0:1]
	v_lshlrev_b64 v[0:1], 11, v[0:1]
	v_or_b32_e32 v7, v0, v40
	v_or_b32_e32 v0, 0x600, v7
	v_lshl_add_u64 v[2:3], s[10:11], 0, v[0:1]
	s_nop 0
	v_mov_b32_e32 v3, v1
	v_lshl_add_u64 v[0:1], s[12:13], 0, v[0:1]
	v_lshlrev_b32_e32 v10, 16, v142
	v_or_b32_e32 v2, 0x640, v7
	v_lshl_add_u64 v[8:9], s[10:11], 0, v[2:3]
	s_nop 0
	v_mul_f32_e32 v8, 0xbfb8aa3b, v10
	v_exp_f32_e32 v8, v8
	v_lshlrev_b32_e32 v7, 16, v143
	v_add_f32_e32 v8, 1.0, v8
	v_div_scale_f32 v9, s[6:7], v8, v8, v10
	v_rcp_f32_e32 v11, v9
	s_nop 0
	v_fma_f32 v16, -v9, v11, 1.0
	v_fmac_f32_e32 v11, v16, v11
	v_div_scale_f32 v16, vcc, v10, v8, v10
	v_mul_f32_e32 v17, v16, v11
	v_fma_f32 v18, -v9, v17, v16
	v_fmac_f32_e32 v17, v18, v11
	v_fma_f32 v9, -v9, v17, v16
	v_div_fmas_f32 v9, v9, v11, v17
	v_div_fixup_f32 v8, v9, v8, v10
	v_mul_f32_e32 v9, 0xbfb8aa3b, v7
	v_exp_f32_e32 v9, v9
	v_mul_f32_e32 v5, v5, v8
	v_mul_f32_e32 v5, v6, v5
	v_mul_f32_e32 v5, v39, v5
	v_add_f32_e32 v9, 1.0, v9
	v_div_scale_f32 v10, s[6:7], v9, v9, v7
	v_rcp_f32_e32 v11, v10
	v_cvt_pk_bf16_f32 v5, v5, s0
	global_store_short v[0:1], v5, off
	v_fma_f32 v16, -v10, v11, 1.0
	v_fmac_f32_e32 v11, v16, v11
	v_div_scale_f32 v16, vcc, v7, v9, v7
	v_mul_f32_e32 v17, v16, v11
	v_fma_f32 v18, -v10, v17, v16
	v_fmac_f32_e32 v17, v18, v11
	v_fma_f32 v10, -v10, v17, v16
	v_div_fmas_f32 v10, v10, v11, v17
	v_div_fixup_f32 v7, v10, v9, v7
	v_mul_f32_e32 v0, v4, v7
	v_mul_f32_e32 v0, v6, v0
	v_mul_f32_e32 v0, v38, v0
	v_cvt_pk_bf16_f32 v4, v0, s0
	v_lshl_add_u64 v[0:1], s[12:13], 0, v[2:3]
	global_store_short v[0:1], v4, off
	v_add_f32_e32 v0, v12, v28
	s_nop 1
	v_add_f32_dpp v0, v0, v0 row_ror:8 row_mask:0xf bank_mask:0xf bound_ctrl:1
	s_nop 1
	v_add_f32_dpp v0, v0, v0 row_ror:4 row_mask:0xf bank_mask:0xf bound_ctrl:1
	s_nop 1
	v_add_f32_dpp v0, v0, v0 row_ror:2 row_mask:0xf bank_mask:0xf bound_ctrl:1
	s_nop 1
	v_add_f32_dpp v0, v0, v0 row_ror:1 row_mask:0xf bank_mask:0xf bound_ctrl:1
	v_mov_b32_e32 v1, v0
	s_nop 1
	v_permlane16_swap_b32_e32 v0, v1
	v_add_f32_e32 v0, v0, v1
	v_fmamk_f32 v4, v0, 0xbc800000, v28
	v_fmamk_f32 v5, v0, 0xbc800000, v12
	v_mul_f32_e32 v0, v4, v4
	v_fmac_f32_e32 v0, v5, v5
	s_nop 1
	v_add_f32_dpp v0, v0, v0 row_ror:8 row_mask:0xf bank_mask:0xf bound_ctrl:1
	s_nop 1
	v_add_f32_dpp v0, v0, v0 row_ror:4 row_mask:0xf bank_mask:0xf bound_ctrl:1
	s_nop 1
	v_add_f32_dpp v0, v0, v0 row_ror:2 row_mask:0xf bank_mask:0xf bound_ctrl:1
; __device__ __forceinline__ unsigned pk2(float lo, float hi) { return pg8::pk_bf16_rne(lo, hi); }
; __device__ __forceinline__ float bf2f(unsigned short u) { return __uint_as_float(((unsigned)u) << 16); }
; __device__ __forceinline__ float half_sum(float v) { v = row16_allsum(v); v = rows_pair_sum(v); return v; }
; __device__ __forceinline__ int crow(int r, int hi) { return (r & 3) + 8 * (r >> 2) + 4 * hi; }
; __device__ __forceinline__ void ret_out(const Params& P, int l, unsigned char* lds, int u, int tid) {
;     ...
;     for (int r = 0; r < 16; ++r) {
;         const float mean = half_sum(o0[r] + o1[r]) * (1.0f / 64.0f);
;         const float d0 = o0[r] - mean, d1 = o1[r] - mean;
;         const float var = half_sum(d0 * d0 + d1 * d1) * (1.0f / 64.0f);
;         const float rstd = 1.0f / sqrtf(var + 1e-5f);
;         const size_t t = tc + c0f + crow(r, hi);
;         const float ga = bf2f(ZR[t * 1024 + 768 + h * 64 + r32]), gb = bf2f(ZR[t * 1024 + 768 + h * 64 + 32 + r32]);
;         const float sa = ga / (1.0f + __expf(-ga)), sb = gb / (1.0f + __expf(-gb));
;         MIX[t * 1024 + 768 + h * 64 + r32] = (bf16_t)(pk2(sa * d0 * rstd * g0, 0.f) & 0xffffu);
;         MIX[t * 1024 + 768 + h * 64 + 32 + r32] = (bf16_t)(pk2(sb * d1 * rstd * g1, 0.f) & 0xffffu);
;     }
	s_nop 1
	v_add_f32_dpp v0, v0, v0 row_ror:1 row_mask:0xf bank_mask:0xf bound_ctrl:1
	v_mov_b32_e32 v1, v0
	s_nop 1
	v_permlane16_swap_b32_e32 v0, v1
	v_add_f32_e32 v0, v0, v1
	v_fmamk_f32 v0, v0, 0x3c800000, v200
	v_cmp_gt_f32_e32 vcc, s43, v0
	v_mul_f32_e32 v1, 0x4f800000, v0
	s_nop 0
	v_cndmask_b32_e32 v0, v0, v1, vcc
	v_sqrt_f32_e32 v1, v0
	s_nop 0
	v_add_u32_e32 v2, -1, v1
	v_fma_f32 v3, -v2, v1, v0
	v_cmp_ge_f32_e64 s[6:7], 0, v3
	v_add_u32_e32 v3, 1, v1
	s_nop 0
	v_cndmask_b32_e64 v2, v1, v2, s[6:7]
	v_fma_f32 v1, -v3, v1, v0
	v_cmp_lt_f32_e64 s[6:7], 0, v1
	s_nop 1
	v_cndmask_b32_e64 v1, v2, v3, s[6:7]
	v_mul_f32_e32 v2, 0x37800000, v1
	v_cndmask_b32_e32 v1, v1, v2, vcc
	v_cmp_class_f32_e32 vcc, v0, v175
	s_nop 1
	v_cndmask_b32_e32 v0, v1, v0, vcc
	v_div_scale_f32 v1, s[6:7], v0, v0, 1.0
	v_rcp_f32_e32 v2, v1
	s_nop 0
	v_fma_f32 v3, -v1, v2, 1.0
	v_fmac_f32_e32 v2, v3, v2
	v_div_scale_f32 v3, vcc, 1.0, v0, 1.0
	v_mul_f32_e32 v6, v3, v2
	v_fma_f32 v7, -v1, v6, v3
	v_fmac_f32_e32 v6, v7, v2
	v_fma_f32 v1, -v1, v6, v3
	v_div_fmas_f32 v1, v1, v2, v6
	v_div_fixup_f32 v6, v1, v0, 1.0
	v_or_b32_e32 v0, 24, v152
	v_mov_b32_e32 v1, v153
	v_lshl_add_u64 v[0:1], v[32:33], 0, v[0:1]
	v_lshlrev_b64 v[0:1], 11, v[0:1]
	v_or_b32_e32 v7, v0, v40
	v_or_b32_e32 v0, 0x600, v7
	v_lshl_add_u64 v[2:3], s[10:11], 0, v[0:1]
	s_nop 0
	v_mov_b32_e32 v3, v1
	v_lshl_add_u64 v[0:1], s[12:13], 0, v[0:1]
	v_lshlrev_b32_e32 v10, 16, v144
	v_or_b32_e32 v2, 0x640, v7
	v_lshl_add_u64 v[8:9], s[10:11], 0, v[2:3]
	s_nop 0
	v_mul_f32_e32 v8, 0xbfb8aa3b, v10
	v_exp_f32_e32 v8, v8
	v_lshlrev_b32_e32 v7, 16, v145
	v_add_f32_e32 v8, 1.0, v8
	v_div_scale_f32 v9, s[6:7], v8, v8, v10
	v_rcp_f32_e32 v11, v9
	s_nop 0
	v_fma_f32 v12, -v9, v11, 1.0
	v_fmac_f32_e32 v11, v12, v11
	v_div_scale_f32 v12, vcc, v10, v8, v10
	v_mul_f32_e32 v16, v12, v11
	v_fma_f32 v17, -v9, v16, v12
	v_fmac_f32_e32 v16, v17, v11
	v_fma_f32 v9, -v9, v16, v12
	v_div_fmas_f32 v9, v9, v11, v16
	v_div_fixup_f32 v8, v9, v8, v10
	v_mul_f32_e32 v9, 0xbfb8aa3b, v7
	v_exp_f32_e32 v9, v9
	v_mul_f32_e32 v5, v5, v8
	v_mul_f32_e32 v5, v6, v5
	v_mul_f32_e32 v5, v39, v5
	v_add_f32_e32 v9, 1.0, v9
	v_div_scale_f32 v10, s[6:7], v9, v9, v7
	v_rcp_f32_e32 v11, v10
	v_cvt_pk_bf16_f32 v5, v5, s0
	global_store_short v[0:1], v5, off
	v_fma_f32 v12, -v10, v11, 1.0
	v_fmac_f32_e32 v11, v12, v11
	v_div_scale_f32 v12, vcc, v7, v9, v7
	v_mul_f32_e32 v16, v12, v11
	v_fma_f32 v17, -v10, v16, v12
	v_fmac_f32_e32 v16, v17, v11
	v_fma_f32 v10, -v10, v16, v12
	v_div_fmas_f32 v10, v10, v11, v16
	v_div_fixup_f32 v7, v10, v9, v7
	v_mul_f32_e32 v0, v4, v7
	v_mul_f32_e32 v0, v6, v0
	v_mul_f32_e32 v0, v38, v0
	v_cvt_pk_bf16_f32 v4, v0, s0
	v_lshl_add_u64 v[0:1], s[12:13], 0, v[2:3]
	global_store_short v[0:1], v4, off
	v_add_f32_e32 v0, v13, v29
	s_nop 1
	v_add_f32_dpp v0, v0, v0 row_ror:8 row_mask:0xf bank_mask:0xf bound_ctrl:1
	s_nop 1
	v_add_f32_dpp v0, v0, v0 row_ror:4 row_mask:0xf bank_mask:0xf bound_ctrl:1
	s_nop 1
	v_add_f32_dpp v0, v0, v0 row_ror:2 row_mask:0xf bank_mask:0xf bound_ctrl:1
	s_nop 1
	v_add_f32_dpp v0, v0, v0 row_ror:1 row_mask:0xf bank_mask:0xf bound_ctrl:1
	v_mov_b32_e32 v1, v0
	s_nop 1
	v_permlane16_swap_b32_e32 v0, v1
	v_add_f32_e32 v0, v0, v1
	v_fmamk_f32 v4, v0, 0xbc800000, v29
	v_fmamk_f32 v5, v0, 0xbc800000, v13
	v_mul_f32_e32 v0, v4, v4
	v_fmac_f32_e32 v0, v5, v5
	s_nop 1
	v_add_f32_dpp v0, v0, v0 row_ror:8 row_mask:0xf bank_mask:0xf bound_ctrl:1
	s_nop 1
	v_add_f32_dpp v0, v0, v0 row_ror:4 row_mask:0xf bank_mask:0xf bound_ctrl:1
	s_nop 1
	v_add_f32_dpp v0, v0, v0 row_ror:2 row_mask:0xf bank_mask:0xf bound_ctrl:1
	s_nop 1
	v_add_f32_dpp v0, v0, v0 row_ror:1 row_mask:0xf bank_mask:0xf bound_ctrl:1
	v_mov_b32_e32 v1, v0
	s_nop 1
	v_permlane16_swap_b32_e32 v0, v1
	v_add_f32_e32 v0, v0, v1
	v_fmamk_f32 v0, v0, 0x3c800000, v200
	v_cmp_gt_f32_e32 vcc, s43, v0
	v_mul_f32_e32 v1, 0x4f800000, v0
	s_nop 0
	v_cndmask_b32_e32 v0, v0, v1, vcc
	v_sqrt_f32_e32 v1, v0
	s_nop 0
	v_add_u32_e32 v2, -1, v1
	v_fma_f32 v3, -v2, v1, v0
	v_cmp_ge_f32_e64 s[6:7], 0, v3
	v_add_u32_e32 v3, 1, v1
	s_nop 0
	v_cndmask_b32_e64 v2, v1, v2, s[6:7]
	v_fma_f32 v1, -v3, v1, v0
	v_cmp_lt_f32_e64 s[6:7], 0, v1
	s_nop 1
	v_cndmask_b32_e64 v1, v2, v3, s[6:7]
	v_mul_f32_e32 v2, 0x37800000, v1
	v_cndmask_b32_e32 v1, v1, v2, vcc
	v_cmp_class_f32_e32 vcc, v0, v175
	s_nop 1
	v_cndmask_b32_e32 v0, v1, v0, vcc
	v_div_scale_f32 v1, s[6:7], v0, v0, 1.0
	v_rcp_f32_e32 v2, v1
	s_nop 0
	v_fma_f32 v3, -v1, v2, 1.0
	v_fmac_f32_e32 v2, v3, v2
	v_div_scale_f32 v3, vcc, 1.0, v0, 1.0
	v_mul_f32_e32 v6, v3, v2
	v_fma_f32 v7, -v1, v6, v3
	v_fmac_f32_e32 v6, v7, v2
	v_fma_f32 v1, -v1, v6, v3
	v_div_fmas_f32 v1, v1, v2, v6
	v_div_fixup_f32 v6, v1, v0, 1.0
	v_or_b32_e32 v0, 25, v152
	v_mov_b32_e32 v1, v153
	v_lshl_add_u64 v[0:1], v[32:33], 0, v[0:1]
	v_lshlrev_b64 v[0:1], 11, v[0:1]
	v_or_b32_e32 v7, v0, v40
	v_or_b32_e32 v0, 0x600, v7
	v_lshl_add_u64 v[2:3], s[10:11], 0, v[0:1]
	s_nop 0
	v_mov_b32_e32 v3, v1
	v_lshl_add_u64 v[0:1], s[12:13], 0, v[0:1]
	v_lshlrev_b32_e32 v10, 16, v146
	v_or_b32_e32 v2, 0x640, v7
	v_lshl_add_u64 v[8:9], s[10:11], 0, v[2:3]
	s_nop 0
	v_mul_f32_e32 v8, 0xbfb8aa3b, v10
	v_exp_f32_e32 v8, v8
	v_lshlrev_b32_e32 v7, 16, v147
	v_add_f32_e32 v8, 1.0, v8
	v_div_scale_f32 v9, s[6:7], v8, v8, v10
	v_rcp_f32_e32 v11, v9
	s_nop 0
	v_fma_f32 v12, -v9, v11, 1.0
	v_fmac_f32_e32 v11, v12, v11
	v_div_scale_f32 v12, vcc, v10, v8, v10
	v_mul_f32_e32 v13, v12, v11
	v_fma_f32 v16, -v9, v13, v12
	v_fmac_f32_e32 v13, v16, v11
	v_fma_f32 v9, -v9, v13, v12
	v_div_fmas_f32 v9, v9, v11, v13
	v_div_fixup_f32 v8, v9, v8, v10
	v_mul_f32_e32 v9, 0xbfb8aa3b, v7
; __device__ __forceinline__ unsigned pk2(float lo, float hi) { return pg8::pk_bf16_rne(lo, hi); }
; __device__ __forceinline__ float bf2f(unsigned short u) { return __uint_as_float(((unsigned)u) << 16); }
; __device__ __forceinline__ float half_sum(float v) { v = row16_allsum(v); v = rows_pair_sum(v); return v; }
; __device__ __forceinline__ int crow(int r, int hi) { return (r & 3) + 8 * (r >> 2) + 4 * hi; }
; __device__ __forceinline__ void ret_out(const Params& P, int l, unsigned char* lds, int u, int tid) {
;     ...
;     for (int r = 0; r < 16; ++r) {
;         const float mean = half_sum(o0[r] + o1[r]) * (1.0f / 64.0f);
;         const float d0 = o0[r] - mean, d1 = o1[r] - mean;
;         const float var = half_sum(d0 * d0 + d1 * d1) * (1.0f / 64.0f);
;         const float rstd = 1.0f / sqrtf(var + 1e-5f);
;         const size_t t = tc + c0f + crow(r, hi);
;         const float ga = bf2f(ZR[t * 1024 + 768 + h * 64 + r32]), gb = bf2f(ZR[t * 1024 + 768 + h * 64 + 32 + r32]);
;         const float sa = ga / (1.0f + __expf(-ga)), sb = gb / (1.0f + __expf(-gb));
;         MIX[t * 1024 + 768 + h * 64 + r32] = (bf16_t)(pk2(sa * d0 * rstd * g0, 0.f) & 0xffffu);
;         MIX[t * 1024 + 768 + h * 64 + 32 + r32] = (bf16_t)(pk2(sb * d1 * rstd * g1, 0.f) & 0xffffu);
;     }
	v_exp_f32_e32 v9, v9
	v_mul_f32_e32 v5, v5, v8
	v_mul_f32_e32 v5, v6, v5
	v_mul_f32_e32 v5, v39, v5
	v_add_f32_e32 v9, 1.0, v9
	v_div_scale_f32 v10, s[6:7], v9, v9, v7
	v_rcp_f32_e32 v11, v10
	v_cvt_pk_bf16_f32 v5, v5, s0
	global_store_short v[0:1], v5, off
	v_fma_f32 v12, -v10, v11, 1.0
	v_fmac_f32_e32 v11, v12, v11
	v_div_scale_f32 v12, vcc, v7, v9, v7
	v_mul_f32_e32 v13, v12, v11
	v_fma_f32 v16, -v10, v13, v12
	v_fmac_f32_e32 v13, v16, v11
	v_fma_f32 v10, -v10, v13, v12
	v_div_fmas_f32 v10, v10, v11, v13
	v_div_fixup_f32 v7, v10, v9, v7
	v_mul_f32_e32 v0, v4, v7
	v_mul_f32_e32 v0, v6, v0
	v_mul_f32_e32 v0, v38, v0
	v_cvt_pk_bf16_f32 v4, v0, s0
	v_lshl_add_u64 v[0:1], s[12:13], 0, v[2:3]
	global_store_short v[0:1], v4, off
	v_add_f32_e32 v0, v14, v30
	s_nop 1
	v_add_f32_dpp v0, v0, v0 row_ror:8 row_mask:0xf bank_mask:0xf bound_ctrl:1
	s_nop 1
	v_add_f32_dpp v0, v0, v0 row_ror:4 row_mask:0xf bank_mask:0xf bound_ctrl:1
	s_nop 1
	v_add_f32_dpp v0, v0, v0 row_ror:2 row_mask:0xf bank_mask:0xf bound_ctrl:1
	s_nop 1
	v_add_f32_dpp v0, v0, v0 row_ror:1 row_mask:0xf bank_mask:0xf bound_ctrl:1
	v_mov_b32_e32 v1, v0
	s_nop 1
	v_permlane16_swap_b32_e32 v0, v1
	v_add_f32_e32 v0, v0, v1
	v_fmamk_f32 v4, v0, 0xbc800000, v30
	v_fmamk_f32 v5, v0, 0xbc800000, v14
	v_mul_f32_e32 v0, v4, v4
	v_fmac_f32_e32 v0, v5, v5
	s_nop 1
	v_add_f32_dpp v0, v0, v0 row_ror:8 row_mask:0xf bank_mask:0xf bound_ctrl:1
	s_nop 1
	v_add_f32_dpp v0, v0, v0 row_ror:4 row_mask:0xf bank_mask:0xf bound_ctrl:1
	s_nop 1
	v_add_f32_dpp v0, v0, v0 row_ror:2 row_mask:0xf bank_mask:0xf bound_ctrl:1
	s_nop 1
	v_add_f32_dpp v0, v0, v0 row_ror:1 row_mask:0xf bank_mask:0xf bound_ctrl:1
	v_mov_b32_e32 v1, v0
	s_nop 1
	v_permlane16_swap_b32_e32 v0, v1
	v_add_f32_e32 v0, v0, v1
	v_fmamk_f32 v0, v0, 0x3c800000, v200
	v_cmp_gt_f32_e32 vcc, s43, v0
	v_mul_f32_e32 v1, 0x4f800000, v0
	s_nop 0
	v_cndmask_b32_e32 v0, v0, v1, vcc
	v_sqrt_f32_e32 v1, v0
	s_nop 0
	v_add_u32_e32 v2, -1, v1
	v_fma_f32 v3, -v2, v1, v0
	v_cmp_ge_f32_e64 s[6:7], 0, v3
	v_add_u32_e32 v3, 1, v1
	s_nop 0
	v_cndmask_b32_e64 v2, v1, v2, s[6:7]
	v_fma_f32 v1, -v3, v1, v0
	v_cmp_lt_f32_e64 s[6:7], 0, v1
	s_nop 1
	v_cndmask_b32_e64 v1, v2, v3, s[6:7]
	v_mul_f32_e32 v2, 0x37800000, v1
	v_cndmask_b32_e32 v1, v1, v2, vcc
	v_cmp_class_f32_e32 vcc, v0, v175
	s_nop 1
	v_cndmask_b32_e32 v0, v1, v0, vcc
	v_div_scale_f32 v1, s[6:7], v0, v0, 1.0
	v_rcp_f32_e32 v2, v1
	s_nop 0
	v_fma_f32 v3, -v1, v2, 1.0
	v_fmac_f32_e32 v2, v3, v2
	v_div_scale_f32 v3, vcc, 1.0, v0, 1.0
	v_mul_f32_e32 v6, v3, v2
	v_fma_f32 v7, -v1, v6, v3
	v_fmac_f32_e32 v6, v7, v2
	v_fma_f32 v1, -v1, v6, v3
	v_div_fmas_f32 v1, v1, v2, v6
	v_div_fixup_f32 v6, v1, v0, 1.0
	v_or_b32_e32 v0, 26, v152
	v_mov_b32_e32 v1, v153
	v_lshl_add_u64 v[0:1], v[32:33], 0, v[0:1]
	v_lshlrev_b64 v[0:1], 11, v[0:1]
	v_or_b32_e32 v7, v0, v40
	v_or_b32_e32 v0, 0x600, v7
	v_lshl_add_u64 v[2:3], s[10:11], 0, v[0:1]
	s_nop 0
	v_mov_b32_e32 v3, v1
	v_lshl_add_u64 v[0:1], s[12:13], 0, v[0:1]
	v_or_b32_e32 v152, 27, v152
	v_lshlrev_b32_e32 v10, 16, v148
	v_or_b32_e32 v2, 0x640, v7
	v_lshl_add_u64 v[8:9], s[10:11], 0, v[2:3]
	s_nop 0
	v_mul_f32_e32 v8, 0xbfb8aa3b, v10
	v_exp_f32_e32 v8, v8
	v_lshlrev_b32_e32 v7, 16, v149
	v_add_f32_e32 v8, 1.0, v8
	v_div_scale_f32 v9, s[6:7], v8, v8, v10
	v_rcp_f32_e32 v11, v9
	s_nop 0
	v_fma_f32 v12, -v9, v11, 1.0
	v_fmac_f32_e32 v11, v12, v11
	v_div_scale_f32 v12, vcc, v10, v8, v10
	v_mul_f32_e32 v13, v12, v11
	v_fma_f32 v14, -v9, v13, v12
	v_fmac_f32_e32 v13, v14, v11
	v_fma_f32 v9, -v9, v13, v12
	v_div_fmas_f32 v9, v9, v11, v13
	v_div_fixup_f32 v8, v9, v8, v10
	v_mul_f32_e32 v9, 0xbfb8aa3b, v7
	v_exp_f32_e32 v9, v9
	v_mul_f32_e32 v5, v5, v8
	v_mul_f32_e32 v5, v6, v5
	v_mul_f32_e32 v5, v39, v5
	v_add_f32_e32 v9, 1.0, v9
	v_div_scale_f32 v10, s[6:7], v9, v9, v7
	v_rcp_f32_e32 v11, v10
	v_cvt_pk_bf16_f32 v5, v5, s0
	global_store_short v[0:1], v5, off
	v_fma_f32 v12, -v10, v11, 1.0
	v_fmac_f32_e32 v11, v12, v11
; __device__ __forceinline__ unsigned pk2(float lo, float hi) { return pg8::pk_bf16_rne(lo, hi); }
; __device__ __forceinline__ float bf2f(unsigned short u) { return __uint_as_float(((unsigned)u) << 16); }
; __device__ __forceinline__ float half_sum(float v) { v = row16_allsum(v); v = rows_pair_sum(v); return v; }
; __device__ __forceinline__ int crow(int r, int hi) { return (r & 3) + 8 * (r >> 2) + 4 * hi; }
; __device__ __forceinline__ void ret_out(const Params& P, int l, unsigned char* lds, int u, int tid) {
;     ...
;     for (int r = 0; r < 16; ++r) {
;         const float mean = half_sum(o0[r] + o1[r]) * (1.0f / 64.0f);
;         const float d0 = o0[r] - mean, d1 = o1[r] - mean;
;         const float var = half_sum(d0 * d0 + d1 * d1) * (1.0f / 64.0f);
;         const float rstd = 1.0f / sqrtf(var + 1e-5f);
;         const size_t t = tc + c0f + crow(r, hi);
;         const float ga = bf2f(ZR[t * 1024 + 768 + h * 64 + r32]), gb = bf2f(ZR[t * 1024 + 768 + h * 64 + 32 + r32]);
;         const float sa = ga / (1.0f + __expf(-ga)), sb = gb / (1.0f + __expf(-gb));
;         MIX[t * 1024 + 768 + h * 64 + r32] = (bf16_t)(pk2(sa * d0 * rstd * g0, 0.f) & 0xffffu);
;         MIX[t * 1024 + 768 + h * 64 + 32 + r32] = (bf16_t)(pk2(sb * d1 * rstd * g1, 0.f) & 0xffffu);
;     }
;     __syncthreads();
	v_div_scale_f32 v12, vcc, v7, v9, v7
	v_mul_f32_e32 v13, v12, v11
	v_fma_f32 v14, -v10, v13, v12
	v_fmac_f32_e32 v13, v14, v11
	v_fma_f32 v10, -v10, v13, v12
	v_div_fmas_f32 v10, v10, v11, v13
	v_div_fixup_f32 v7, v10, v9, v7
	v_mul_f32_e32 v0, v4, v7
	v_mul_f32_e32 v0, v6, v0
	v_mul_f32_e32 v0, v38, v0
	v_cvt_pk_bf16_f32 v4, v0, s0
	v_lshl_add_u64 v[0:1], s[12:13], 0, v[2:3]
	global_store_short v[0:1], v4, off
	v_add_f32_e32 v0, v15, v31
	s_nop 1
	v_add_f32_dpp v0, v0, v0 row_ror:8 row_mask:0xf bank_mask:0xf bound_ctrl:1
	s_nop 1
	v_add_f32_dpp v0, v0, v0 row_ror:4 row_mask:0xf bank_mask:0xf bound_ctrl:1
	s_nop 1
	v_add_f32_dpp v0, v0, v0 row_ror:2 row_mask:0xf bank_mask:0xf bound_ctrl:1
	s_nop 1
	v_add_f32_dpp v0, v0, v0 row_ror:1 row_mask:0xf bank_mask:0xf bound_ctrl:1
	v_mov_b32_e32 v1, v0
	s_nop 1
	v_permlane16_swap_b32_e32 v0, v1
	v_add_f32_e32 v0, v0, v1
	v_fmac_f32_e32 v31, 0xbc800000, v0
	v_fmac_f32_e32 v15, 0xbc800000, v0
	v_mul_f32_e32 v0, v31, v31
	v_fmac_f32_e32 v0, v15, v15
	s_nop 1
	v_add_f32_dpp v0, v0, v0 row_ror:8 row_mask:0xf bank_mask:0xf bound_ctrl:1
	s_nop 1
	v_add_f32_dpp v0, v0, v0 row_ror:4 row_mask:0xf bank_mask:0xf bound_ctrl:1
	s_nop 1
	v_add_f32_dpp v0, v0, v0 row_ror:2 row_mask:0xf bank_mask:0xf bound_ctrl:1
	s_nop 1
	v_add_f32_dpp v0, v0, v0 row_ror:1 row_mask:0xf bank_mask:0xf bound_ctrl:1
	v_mov_b32_e32 v1, v0
	s_nop 1
	v_permlane16_swap_b32_e32 v0, v1
	v_add_f32_e32 v0, v0, v1
	v_fmamk_f32 v0, v0, 0x3c800000, v200
	v_cmp_gt_f32_e32 vcc, s43, v0
	v_mul_f32_e32 v1, 0x4f800000, v0
	s_nop 0
	v_cndmask_b32_e32 v0, v0, v1, vcc
	v_sqrt_f32_e32 v1, v0
	s_nop 0
	v_add_u32_e32 v2, -1, v1
	v_fma_f32 v3, -v2, v1, v0
	v_cmp_ge_f32_e64 s[6:7], 0, v3
	v_add_u32_e32 v3, 1, v1
	s_nop 0
	v_cndmask_b32_e64 v2, v1, v2, s[6:7]
	v_fma_f32 v1, -v3, v1, v0
	v_cmp_lt_f32_e64 s[6:7], 0, v1
	s_nop 1
	v_cndmask_b32_e64 v1, v2, v3, s[6:7]
	v_mul_f32_e32 v2, 0x37800000, v1
	v_cndmask_b32_e32 v1, v1, v2, vcc
	v_cmp_class_f32_e32 vcc, v0, v175
	s_nop 1
	v_cndmask_b32_e32 v0, v1, v0, vcc
	v_div_scale_f32 v1, s[6:7], v0, v0, 1.0
	v_rcp_f32_e32 v2, v1
	s_nop 0
	v_fma_f32 v3, -v1, v2, 1.0
	v_fmac_f32_e32 v2, v3, v2
	v_div_scale_f32 v3, vcc, 1.0, v0, 1.0
	v_mul_f32_e32 v4, v3, v2
	v_fma_f32 v5, -v1, v4, v3
	v_fmac_f32_e32 v4, v5, v2
	v_fma_f32 v1, -v1, v4, v3
	v_div_fmas_f32 v1, v1, v2, v4
	v_div_fixup_f32 v4, v1, v0, 1.0
	v_lshl_add_u64 v[0:1], v[32:33], 0, v[152:153]
	v_lshlrev_b64 v[0:1], 11, v[0:1]
	v_or_b32_e32 v5, v0, v40
	v_or_b32_e32 v0, 0x600, v5
	v_lshl_add_u64 v[2:3], s[10:11], 0, v[0:1]
	s_nop 0
	v_mov_b32_e32 v3, v1
	v_lshl_add_u64 v[0:1], s[12:13], 0, v[0:1]
	v_lshlrev_b32_e32 v8, 16, v150
	v_or_b32_e32 v2, 0x640, v5
	v_lshl_add_u64 v[6:7], s[10:11], 0, v[2:3]
	s_nop 0
	v_mul_f32_e32 v6, 0xbfb8aa3b, v8
	v_exp_f32_e32 v6, v6
	v_lshlrev_b32_e32 v5, 16, v151
	v_add_f32_e32 v6, 1.0, v6
	v_div_scale_f32 v7, s[6:7], v6, v6, v8
	v_rcp_f32_e32 v9, v7
	s_nop 0
	v_fma_f32 v10, -v7, v9, 1.0
	v_fmac_f32_e32 v9, v10, v9
	v_div_scale_f32 v10, vcc, v8, v6, v8
	v_mul_f32_e32 v11, v10, v9
	v_fma_f32 v12, -v7, v11, v10
	v_fmac_f32_e32 v11, v12, v9
	v_fma_f32 v7, -v7, v11, v10
	v_div_fmas_f32 v7, v7, v9, v11
	v_div_fixup_f32 v6, v7, v6, v8
	v_mul_f32_e32 v7, 0xbfb8aa3b, v5
	v_exp_f32_e32 v7, v7
	v_mul_f32_e32 v6, v15, v6
	v_mul_f32_e32 v6, v4, v6
	v_mul_f32_e32 v6, v39, v6
	v_add_f32_e32 v7, 1.0, v7
	v_div_scale_f32 v8, s[6:7], v7, v7, v5
	v_rcp_f32_e32 v9, v8
	v_cvt_pk_bf16_f32 v6, v6, s0
	global_store_short v[0:1], v6, off
	v_fma_f32 v10, -v8, v9, 1.0
	v_fmac_f32_e32 v9, v10, v9
	v_div_scale_f32 v10, vcc, v5, v7, v5
	v_mul_f32_e32 v11, v10, v9
	v_fma_f32 v12, -v8, v11, v10
	v_fmac_f32_e32 v11, v12, v9
	v_fma_f32 v8, -v8, v11, v10
	v_div_fmas_f32 v8, v8, v9, v11
	v_div_fixup_f32 v5, v8, v7, v5
	v_mul_f32_e32 v0, v31, v5
	v_mul_f32_e32 v0, v4, v0
	v_mul_f32_e32 v0, v38, v0
	v_cvt_pk_bf16_f32 v4, v0, s0
	v_lshl_add_u64 v[0:1], s[12:13], 0, v[2:3]
	global_store_short v[0:1], v4, off
	s_barrier
